# q/kv up-projection epilogue rewritten by hand (K+rope, V, q paths; loads hoisted); fixed a load-vs-VALU register race in the q path
# speedup vs baseline: 1.0808x; 1.0112x over previous
; __device__ __forceinline__ int otid() { int t = (int)threadIdx.x; asm volatile("" : "+v"(t)); return t; }
; __device__ __forceinline__ unsigned cvt_pk_bf16(float lo, float hi) { unsigned r; asm volatile("v_cvt_pk_bf16_f32 %0, %1, %2" : "=v"(r) : "v"(lo), "v"(hi)); return r; }
;     __device__ __forceinline__ void operator()(const f32x4 (&acc)[2][2][4][2], const Unit& u, int wr, int wc, int fr, int fq) const {
;         { const int ln_ = otid() & 63; fr = ln_ & 15; fq = ln_ >> 4; }
;         const size_t rowb = (size_t)u.pm * BM + wr * 64 + fr; const int col0 = u.pn * BM + wc * 32 + 8 * fq;
; #pragma unroll
;         for (int ai = 0; ai < 2; ++ai)
; #pragma unroll
;             for (int m = 0; m < 4; ++m) { const size_t row = rowb + ai * HALF + m * 16;
; #pragma unroll
;                 for (int bj = 0; bj < 2; ++bj) { const u32x4 sg = *(const u32x4*)(SIG + row * 2048 + 1024 + col0 + bj * HALF);
;                     f32x4 v0 = acc[ai][bj][m][0], v1 = acc[ai][bj][m][1];
;                     v0[0] *= bf_lo(sg.x); v0[1] *= bf_hi(sg.x); v0[2] *= bf_lo(sg.y); v0[3] *= bf_hi(sg.y);
;                     v1[0] *= bf_lo(sg.z); v1[1] *= bf_hi(sg.z); v1[2] *= bf_lo(sg.w); v1[3] *= bf_hi(sg.w);
;                     u32x4 w; w.x = cvt_pk_bf16(v0[0], v0[1]); w.y = cvt_pk_bf16(v0[2], v0[3]); w.z = cvt_pk_bf16(v1[0], v1[1]); w.w = cvt_pk_bf16(v1[2], v1[3]);
;                     *(u32x4*)(O + row * 1024 + col0 + bj * HALF) = w; } }
.LBB0_217:
	v_mov_b32_e32 v130, v221
	s_lshl_b64 s[2:3], s[46:47], 8
	s_add_u32 s2, s2, s56
	v_and_or_b32 v132, v130, 15, s2
	v_lshrrev_b32_e32 v130, 1, v130
	s_addc_u32 s3, s3, s60
	v_and_or_b32 v130, v130, 24, s57
	v_mov_b32_e32 v133, s3
	v_or_b32_e32 v130, s17, v130
	v_ashrrev_i32_e32 v131, 31, v130
	v_lshlrev_b64 v[134:135], 12, v[132:133]
	v_lshl_add_u64 v[134:135], s[12:13], 0, v[134:135]
	v_lshlrev_b64 v[130:131], 1, v[130:131]
	v_lshl_add_u64 v[150:151], v[134:135], 0, v[130:131]
	v_lshlrev_b64 v[148:149], 11, v[132:133]
	v_lshl_add_u64 v[148:149], s[92:93], 0, v[148:149]
	v_lshl_add_u64 v[148:149], v[148:149], 0, v[130:131]
	global_load_dwordx4 v[234:237], v[150:151], off offset:2048
	global_load_dwordx4 v[238:241], v[150:151], off offset:2304
	v_add_co_u32_e32 v150, vcc, 0x10000, v150
	s_nop 1
	v_addc_co_u32_e32 v151, vcc, 0, v151, vcc
	global_load_dwordx4 v[242:245], v[150:151], off offset:2048
	global_load_dwordx4 v[246:249], v[150:151], off offset:2304
	v_add_co_u32_e32 v150, vcc, 0x10000, v150
	s_nop 1
	v_addc_co_u32_e32 v151, vcc, 0, v151, vcc
	global_load_dwordx4 v[134:137], v[150:151], off offset:2048
	s_waitcnt vmcnt(4)
	v_lshlrev_b32_e32 v250, 16, v234
	v_and_b32_e32 v251, 0xffff0000, v234
	v_mul_f32_e32 v126, v126, v250
	v_mul_f32_e32 v127, v127, v251
	v_lshlrev_b32_e32 v252, 16, v235
	v_and_b32_e32 v253, 0xffff0000, v235
	v_mul_f32_e32 v128, v128, v252
	v_mul_f32_e32 v129, v129, v253
	v_lshlrev_b32_e32 v250, 16, v236
	v_and_b32_e32 v251, 0xffff0000, v236
	v_mul_f32_e32 v122, v122, v250
	v_mul_f32_e32 v123, v123, v251
	v_lshlrev_b32_e32 v252, 16, v237
	v_and_b32_e32 v253, 0xffff0000, v237
	v_mul_f32_e32 v124, v124, v252
	v_mul_f32_e32 v125, v125, v253
	v_cvt_pk_bf16_f32 v234, v126, v127
	v_cvt_pk_bf16_f32 v235, v128, v129
	v_cvt_pk_bf16_f32 v236, v122, v123
	v_cvt_pk_bf16_f32 v237, v124, v125
	global_store_dwordx4 v[148:149], v[234:237], off
	s_nop 1
	global_load_dwordx4 v[234:237], v[150:151], off offset:2304
	s_waitcnt vmcnt(5)
	v_lshlrev_b32_e32 v250, 16, v238
	v_and_b32_e32 v251, 0xffff0000, v238
	v_mul_f32_e32 v118, v118, v250
	v_mul_f32_e32 v119, v119, v251
	v_lshlrev_b32_e32 v252, 16, v239
	v_and_b32_e32 v253, 0xffff0000, v239
	v_mul_f32_e32 v120, v120, v252
	v_mul_f32_e32 v121, v121, v253
	v_lshlrev_b32_e32 v250, 16, v240
	v_and_b32_e32 v251, 0xffff0000, v240
	v_mul_f32_e32 v114, v114, v250
	v_mul_f32_e32 v115, v115, v251
	v_lshlrev_b32_e32 v252, 16, v241
	v_and_b32_e32 v253, 0xffff0000, v241
	v_mul_f32_e32 v116, v116, v252
	v_mul_f32_e32 v117, v117, v253
	v_cvt_pk_bf16_f32 v238, v118, v119
	v_cvt_pk_bf16_f32 v239, v120, v121
	v_cvt_pk_bf16_f32 v240, v114, v115
	v_cvt_pk_bf16_f32 v241, v116, v117
	global_store_dwordx4 v[148:149], v[238:241], off offset:256
	s_nop 1
	v_add_co_u32_e32 v148, vcc, 0x8000, v148
	s_nop 1
	v_addc_co_u32_e32 v149, vcc, 0, v149, vcc
	v_add_co_u32_e32 v150, vcc, 0x10000, v150
	s_nop 1
	v_addc_co_u32_e32 v151, vcc, 0, v151, vcc
	global_load_dwordx4 v[238:241], v[150:151], off offset:2048
	s_waitcnt vmcnt(6)
	v_lshlrev_b32_e32 v250, 16, v242
	v_and_b32_e32 v251, 0xffff0000, v242
	v_mul_f32_e32 v110, v110, v250
	v_mul_f32_e32 v111, v111, v251
	v_lshlrev_b32_e32 v252, 16, v243
	v_and_b32_e32 v253, 0xffff0000, v243
	v_mul_f32_e32 v112, v112, v252
	v_mul_f32_e32 v113, v113, v253
	v_lshlrev_b32_e32 v250, 16, v244
	v_and_b32_e32 v251, 0xffff0000, v244
	v_mul_f32_e32 v106, v106, v250
	v_mul_f32_e32 v107, v107, v251
	v_lshlrev_b32_e32 v252, 16, v245
	v_and_b32_e32 v253, 0xffff0000, v245
	v_mul_f32_e32 v108, v108, v252
	v_mul_f32_e32 v109, v109, v253
	v_cvt_pk_bf16_f32 v242, v110, v111
	v_cvt_pk_bf16_f32 v243, v112, v113
	v_cvt_pk_bf16_f32 v244, v106, v107
	v_cvt_pk_bf16_f32 v245, v108, v109
	global_store_dwordx4 v[148:149], v[242:245], off
	s_nop 1
	global_load_dwordx4 v[242:245], v[150:151], off offset:2304
	s_waitcnt vmcnt(7)
	v_lshlrev_b32_e32 v250, 16, v246
	v_and_b32_e32 v251, 0xffff0000, v246
	v_mul_f32_e32 v102, v102, v250
	v_mul_f32_e32 v103, v103, v251
	v_lshlrev_b32_e32 v252, 16, v247
	v_and_b32_e32 v253, 0xffff0000, v247
	v_mul_f32_e32 v104, v104, v252
	v_mul_f32_e32 v105, v105, v253
	v_lshlrev_b32_e32 v250, 16, v248
	v_and_b32_e32 v251, 0xffff0000, v248
	v_mul_f32_e32 v98, v98, v250
	v_mul_f32_e32 v99, v99, v251
	v_lshlrev_b32_e32 v252, 16, v249
	v_and_b32_e32 v253, 0xffff0000, v249
	v_mul_f32_e32 v100, v100, v252
	v_mul_f32_e32 v101, v101, v253
	v_cvt_pk_bf16_f32 v246, v102, v103
	v_cvt_pk_bf16_f32 v247, v104, v105
	v_cvt_pk_bf16_f32 v248, v98, v99
	v_cvt_pk_bf16_f32 v249, v100, v101
	global_store_dwordx4 v[148:149], v[246:249], off offset:256
	s_nop 1
	v_add_co_u32_e32 v148, vcc, 0x8000, v148
	s_nop 1
	v_addc_co_u32_e32 v149, vcc, 0, v149, vcc
	v_add_co_u32_e32 v150, vcc, 0x50000, v150
	s_nop 1
	v_addc_co_u32_e32 v151, vcc, 0, v151, vcc
	global_load_dwordx4 v[246:249], v[150:151], off offset:2048
	s_waitcnt vmcnt(8)
	v_lshlrev_b32_e32 v250, 16, v134
	v_and_b32_e32 v251, 0xffff0000, v134
	v_mul_f32_e32 v94, v94, v250
	v_mul_f32_e32 v95, v95, v251
	v_lshlrev_b32_e32 v252, 16, v135
	v_and_b32_e32 v253, 0xffff0000, v135
	v_mul_f32_e32 v96, v96, v252
	v_mul_f32_e32 v97, v97, v253
	v_lshlrev_b32_e32 v250, 16, v136
	v_and_b32_e32 v251, 0xffff0000, v136
	v_mul_f32_e32 v90, v90, v250
	v_mul_f32_e32 v91, v91, v251
	v_lshlrev_b32_e32 v252, 16, v137
	v_and_b32_e32 v253, 0xffff0000, v137
	v_mul_f32_e32 v92, v92, v252
	v_mul_f32_e32 v93, v93, v253
	v_cvt_pk_bf16_f32 v134, v94, v95
	v_cvt_pk_bf16_f32 v135, v96, v97
	v_cvt_pk_bf16_f32 v136, v90, v91
	v_cvt_pk_bf16_f32 v137, v92, v93
	global_store_dwordx4 v[148:149], v[134:137], off
	s_nop 1
	global_load_dwordx4 v[134:137], v[150:151], off offset:2304
	s_waitcnt vmcnt(8)
; __device__ __forceinline__ unsigned cvt_pk_bf16(float lo, float hi) { unsigned r; asm volatile("v_cvt_pk_bf16_f32 %0, %1, %2" : "=v"(r) : "v"(lo), "v"(hi)); return r; }
;     __device__ __forceinline__ void operator()(const f32x4 (&acc)[2][2][4][2], const Unit& u, int wr, int wc, int fr, int fq) const {
;     ...
;             for (int m = 0; m < 4; ++m) { const size_t row = rowb + ai * HALF + m * 16;
; #pragma unroll
;                 for (int bj = 0; bj < 2; ++bj) { const u32x4 sg = *(const u32x4*)(SIG + row * 2048 + 1024 + col0 + bj * HALF);
;                     f32x4 v0 = acc[ai][bj][m][0], v1 = acc[ai][bj][m][1];
;                     v0[0] *= bf_lo(sg.x); v0[1] *= bf_hi(sg.x); v0[2] *= bf_lo(sg.y); v0[3] *= bf_hi(sg.y);
;                     v1[0] *= bf_lo(sg.z); v1[1] *= bf_hi(sg.z); v1[2] *= bf_lo(sg.w); v1[3] *= bf_hi(sg.w);
;                     u32x4 w; w.x = cvt_pk_bf16(v0[0], v0[1]); w.y = cvt_pk_bf16(v0[2], v0[3]); w.z = cvt_pk_bf16(v1[0], v1[1]); w.w = cvt_pk_bf16(v1[2], v1[3]);
;                     *(u32x4*)(O + row * 1024 + col0 + bj * HALF) = w; } }
	v_lshlrev_b32_e32 v250, 16, v234
	v_and_b32_e32 v251, 0xffff0000, v234
	v_mul_f32_e32 v86, v86, v250
	v_mul_f32_e32 v87, v87, v251
	v_lshlrev_b32_e32 v252, 16, v235
	v_and_b32_e32 v253, 0xffff0000, v235
	v_mul_f32_e32 v88, v88, v252
	v_mul_f32_e32 v89, v89, v253
	v_lshlrev_b32_e32 v250, 16, v236
	v_and_b32_e32 v251, 0xffff0000, v236
	v_mul_f32_e32 v82, v82, v250
	v_mul_f32_e32 v83, v83, v251
	v_lshlrev_b32_e32 v252, 16, v237
	v_and_b32_e32 v253, 0xffff0000, v237
	v_mul_f32_e32 v84, v84, v252
	v_mul_f32_e32 v85, v85, v253
	v_cvt_pk_bf16_f32 v234, v86, v87
	v_cvt_pk_bf16_f32 v235, v88, v89
	v_cvt_pk_bf16_f32 v236, v82, v83
	v_cvt_pk_bf16_f32 v237, v84, v85
	global_store_dwordx4 v[148:149], v[234:237], off offset:256
	s_nop 1
	v_add_co_u32_e32 v148, vcc, 0x8000, v148
	s_nop 1
	v_addc_co_u32_e32 v149, vcc, 0, v149, vcc
	v_add_co_u32_e32 v150, vcc, 0x10000, v150
	s_nop 1
	v_addc_co_u32_e32 v151, vcc, 0, v151, vcc
	global_load_dwordx4 v[234:237], v[150:151], off offset:2048
	s_waitcnt vmcnt(8)
	v_lshlrev_b32_e32 v250, 16, v238
	v_and_b32_e32 v251, 0xffff0000, v238
	v_mul_f32_e32 v78, v78, v250
	v_mul_f32_e32 v79, v79, v251
	v_lshlrev_b32_e32 v252, 16, v239
	v_and_b32_e32 v253, 0xffff0000, v239
	v_mul_f32_e32 v80, v80, v252
	v_mul_f32_e32 v81, v81, v253
	v_lshlrev_b32_e32 v250, 16, v240
	v_and_b32_e32 v251, 0xffff0000, v240
	v_mul_f32_e32 v74, v74, v250
	v_mul_f32_e32 v75, v75, v251
	v_lshlrev_b32_e32 v252, 16, v241
	v_and_b32_e32 v253, 0xffff0000, v241
	v_mul_f32_e32 v76, v76, v252
	v_mul_f32_e32 v77, v77, v253
	v_cvt_pk_bf16_f32 v238, v78, v79
	v_cvt_pk_bf16_f32 v239, v80, v81
	v_cvt_pk_bf16_f32 v240, v74, v75
	v_cvt_pk_bf16_f32 v241, v76, v77
	global_store_dwordx4 v[148:149], v[238:241], off
	s_nop 1
	global_load_dwordx4 v[238:241], v[150:151], off offset:2304
	s_waitcnt vmcnt(8)
	v_lshlrev_b32_e32 v250, 16, v242
	v_and_b32_e32 v251, 0xffff0000, v242
	v_mul_f32_e32 v70, v70, v250
	v_mul_f32_e32 v71, v71, v251
	v_lshlrev_b32_e32 v252, 16, v243
	v_and_b32_e32 v253, 0xffff0000, v243
	v_mul_f32_e32 v72, v72, v252
	v_mul_f32_e32 v73, v73, v253
	v_lshlrev_b32_e32 v250, 16, v244
	v_and_b32_e32 v251, 0xffff0000, v244
	v_mul_f32_e32 v66, v66, v250
	v_mul_f32_e32 v67, v67, v251
	v_lshlrev_b32_e32 v252, 16, v245
	v_and_b32_e32 v253, 0xffff0000, v245
	v_mul_f32_e32 v68, v68, v252
	v_mul_f32_e32 v69, v69, v253
	v_cvt_pk_bf16_f32 v242, v70, v71
	v_cvt_pk_bf16_f32 v243, v72, v73
	v_cvt_pk_bf16_f32 v244, v66, v67
	v_cvt_pk_bf16_f32 v245, v68, v69
	global_store_dwordx4 v[148:149], v[242:245], off offset:256
	s_nop 1
	v_add_co_u32_e32 v148, vcc, 0x28000, v148
	s_nop 1
	v_addc_co_u32_e32 v149, vcc, 0, v149, vcc
	v_add_co_u32_e32 v150, vcc, 0x10000, v150
	s_nop 1
	v_addc_co_u32_e32 v151, vcc, 0, v151, vcc
	global_load_dwordx4 v[242:245], v[150:151], off offset:2048
	s_waitcnt vmcnt(8)
	v_lshlrev_b32_e32 v250, 16, v246
	v_and_b32_e32 v251, 0xffff0000, v246
	v_mul_f32_e32 v62, v62, v250
	v_mul_f32_e32 v63, v63, v251
	v_lshlrev_b32_e32 v252, 16, v247
	v_and_b32_e32 v253, 0xffff0000, v247
	v_mul_f32_e32 v64, v64, v252
	v_mul_f32_e32 v65, v65, v253
	v_lshlrev_b32_e32 v250, 16, v248
	v_and_b32_e32 v251, 0xffff0000, v248
	v_mul_f32_e32 v58, v58, v250
	v_mul_f32_e32 v59, v59, v251
	v_lshlrev_b32_e32 v252, 16, v249
	v_and_b32_e32 v253, 0xffff0000, v249
	v_mul_f32_e32 v60, v60, v252
	v_mul_f32_e32 v61, v61, v253
	v_cvt_pk_bf16_f32 v246, v62, v63
	v_cvt_pk_bf16_f32 v247, v64, v65
	v_cvt_pk_bf16_f32 v248, v58, v59
	v_cvt_pk_bf16_f32 v249, v60, v61
	global_store_dwordx4 v[148:149], v[246:249], off
	s_nop 1
	global_load_dwordx4 v[246:249], v[150:151], off offset:2304
	s_waitcnt vmcnt(8)
	v_lshlrev_b32_e32 v250, 16, v134
	v_and_b32_e32 v251, 0xffff0000, v134
	v_mul_f32_e32 v54, v54, v250
	v_mul_f32_e32 v55, v55, v251
	v_lshlrev_b32_e32 v252, 16, v135
	v_and_b32_e32 v253, 0xffff0000, v135
	v_mul_f32_e32 v56, v56, v252
	v_mul_f32_e32 v57, v57, v253
	v_lshlrev_b32_e32 v250, 16, v136
	v_and_b32_e32 v251, 0xffff0000, v136
	v_mul_f32_e32 v50, v50, v250
	v_mul_f32_e32 v51, v51, v251
	v_lshlrev_b32_e32 v252, 16, v137
	v_and_b32_e32 v253, 0xffff0000, v137
	v_mul_f32_e32 v52, v52, v252
	v_mul_f32_e32 v53, v53, v253
	v_cvt_pk_bf16_f32 v134, v54, v55
	v_cvt_pk_bf16_f32 v135, v56, v57
	v_cvt_pk_bf16_f32 v136, v50, v51
	v_cvt_pk_bf16_f32 v137, v52, v53
	global_store_dwordx4 v[148:149], v[134:137], off offset:256
	s_nop 1
	v_add_co_u32_e32 v148, vcc, 0x8000, v148
	s_nop 1
	v_addc_co_u32_e32 v149, vcc, 0, v149, vcc
	v_add_co_u32_e32 v150, vcc, 0x10000, v150
	s_nop 1
	v_addc_co_u32_e32 v151, vcc, 0, v151, vcc
	global_load_dwordx4 v[134:137], v[150:151], off offset:2048
	s_waitcnt vmcnt(8)
; __device__ __forceinline__ unsigned cvt_pk_bf16(float lo, float hi) { unsigned r; asm volatile("v_cvt_pk_bf16_f32 %0, %1, %2" : "=v"(r) : "v"(lo), "v"(hi)); return r; }
;     __device__ __forceinline__ void operator()(const f32x4 (&acc)[2][2][4][2], const Unit& u, int wr, int wc, int fr, int fq) const {
;     ...
;             for (int m = 0; m < 4; ++m) { const size_t row = rowb + ai * HALF + m * 16;
; #pragma unroll
;                 for (int bj = 0; bj < 2; ++bj) { const u32x4 sg = *(const u32x4*)(SIG + row * 2048 + 1024 + col0 + bj * HALF);
;                     f32x4 v0 = acc[ai][bj][m][0], v1 = acc[ai][bj][m][1];
;                     v0[0] *= bf_lo(sg.x); v0[1] *= bf_hi(sg.x); v0[2] *= bf_lo(sg.y); v0[3] *= bf_hi(sg.y);
;                     v1[0] *= bf_lo(sg.z); v1[1] *= bf_hi(sg.z); v1[2] *= bf_lo(sg.w); v1[3] *= bf_hi(sg.w);
;                     u32x4 w; w.x = cvt_pk_bf16(v0[0], v0[1]); w.y = cvt_pk_bf16(v0[2], v0[3]); w.z = cvt_pk_bf16(v1[0], v1[1]); w.w = cvt_pk_bf16(v1[2], v1[3]);
;                     *(u32x4*)(O + row * 1024 + col0 + bj * HALF) = w; } }
	v_lshlrev_b32_e32 v250, 16, v234
	v_and_b32_e32 v251, 0xffff0000, v234
	v_mul_f32_e32 v46, v46, v250
	v_mul_f32_e32 v47, v47, v251
	v_lshlrev_b32_e32 v252, 16, v235
	v_and_b32_e32 v253, 0xffff0000, v235
	v_mul_f32_e32 v48, v48, v252
	v_mul_f32_e32 v49, v49, v253
	v_lshlrev_b32_e32 v250, 16, v236
	v_and_b32_e32 v251, 0xffff0000, v236
	v_mul_f32_e32 v42, v42, v250
	v_mul_f32_e32 v43, v43, v251
	v_lshlrev_b32_e32 v252, 16, v237
	v_and_b32_e32 v253, 0xffff0000, v237
	v_mul_f32_e32 v44, v44, v252
	v_mul_f32_e32 v45, v45, v253
	v_cvt_pk_bf16_f32 v234, v46, v47
	v_cvt_pk_bf16_f32 v235, v48, v49
	v_cvt_pk_bf16_f32 v236, v42, v43
	v_cvt_pk_bf16_f32 v237, v44, v45
	global_store_dwordx4 v[148:149], v[234:237], off
	s_nop 1
	global_load_dwordx4 v[234:237], v[150:151], off offset:2304
	s_waitcnt vmcnt(8)
	v_lshlrev_b32_e32 v250, 16, v238
	v_and_b32_e32 v251, 0xffff0000, v238
	v_mul_f32_e32 v38, v38, v250
	v_mul_f32_e32 v39, v39, v251
	v_lshlrev_b32_e32 v252, 16, v239
	v_and_b32_e32 v253, 0xffff0000, v239
	v_mul_f32_e32 v40, v40, v252
	v_mul_f32_e32 v41, v41, v253
	v_lshlrev_b32_e32 v250, 16, v240
	v_and_b32_e32 v251, 0xffff0000, v240
	v_mul_f32_e32 v34, v34, v250
	v_mul_f32_e32 v35, v35, v251
	v_lshlrev_b32_e32 v252, 16, v241
	v_and_b32_e32 v253, 0xffff0000, v241
	v_mul_f32_e32 v36, v36, v252
	v_mul_f32_e32 v37, v37, v253
	v_cvt_pk_bf16_f32 v238, v38, v39
	v_cvt_pk_bf16_f32 v239, v40, v41
	v_cvt_pk_bf16_f32 v240, v34, v35
	v_cvt_pk_bf16_f32 v241, v36, v37
	global_store_dwordx4 v[148:149], v[238:241], off offset:256
	s_nop 1
	v_add_co_u32_e32 v148, vcc, 0x8000, v148
	s_nop 1
	v_addc_co_u32_e32 v149, vcc, 0, v149, vcc
	s_waitcnt vmcnt(7)
	v_lshlrev_b32_e32 v250, 16, v242
	v_and_b32_e32 v251, 0xffff0000, v242
	v_mul_f32_e32 v30, v30, v250
	v_mul_f32_e32 v31, v31, v251
	v_lshlrev_b32_e32 v252, 16, v243
	v_and_b32_e32 v253, 0xffff0000, v243
	v_mul_f32_e32 v32, v32, v252
	v_mul_f32_e32 v33, v33, v253
	v_lshlrev_b32_e32 v250, 16, v244
	v_and_b32_e32 v251, 0xffff0000, v244
	v_mul_f32_e32 v26, v26, v250
	v_mul_f32_e32 v27, v27, v251
	v_lshlrev_b32_e32 v252, 16, v245
	v_and_b32_e32 v253, 0xffff0000, v245
	v_mul_f32_e32 v28, v28, v252
	v_mul_f32_e32 v29, v29, v253
	v_cvt_pk_bf16_f32 v242, v30, v31
	v_cvt_pk_bf16_f32 v243, v32, v33
	v_cvt_pk_bf16_f32 v244, v26, v27
	v_cvt_pk_bf16_f32 v245, v28, v29
	global_store_dwordx4 v[148:149], v[242:245], off
	s_nop 1
	s_waitcnt vmcnt(6)
	v_lshlrev_b32_e32 v250, 16, v246
	v_and_b32_e32 v251, 0xffff0000, v246
	v_mul_f32_e32 v22, v22, v250
	v_mul_f32_e32 v23, v23, v251
	v_lshlrev_b32_e32 v252, 16, v247
	v_and_b32_e32 v253, 0xffff0000, v247
	v_mul_f32_e32 v24, v24, v252
	v_mul_f32_e32 v25, v25, v253
	v_lshlrev_b32_e32 v250, 16, v248
	v_and_b32_e32 v251, 0xffff0000, v248
	v_mul_f32_e32 v18, v18, v250
	v_mul_f32_e32 v19, v19, v251
	v_lshlrev_b32_e32 v252, 16, v249
	v_and_b32_e32 v253, 0xffff0000, v249
	v_mul_f32_e32 v20, v20, v252
	v_mul_f32_e32 v21, v21, v253
	v_cvt_pk_bf16_f32 v246, v22, v23
	v_cvt_pk_bf16_f32 v247, v24, v25
	v_cvt_pk_bf16_f32 v248, v18, v19
	v_cvt_pk_bf16_f32 v249, v20, v21
	global_store_dwordx4 v[148:149], v[246:249], off offset:256
	s_nop 1
	v_add_co_u32_e32 v148, vcc, 0x8000, v148
	s_nop 1
	v_addc_co_u32_e32 v149, vcc, 0, v149, vcc
	s_waitcnt vmcnt(5)
	v_lshlrev_b32_e32 v250, 16, v134
	v_and_b32_e32 v251, 0xffff0000, v134
	v_mul_f32_e32 v14, v14, v250
	v_mul_f32_e32 v15, v15, v251
	v_lshlrev_b32_e32 v252, 16, v135
	v_and_b32_e32 v253, 0xffff0000, v135
	v_mul_f32_e32 v16, v16, v252
	v_mul_f32_e32 v17, v17, v253
	v_lshlrev_b32_e32 v250, 16, v136
	v_and_b32_e32 v251, 0xffff0000, v136
	v_mul_f32_e32 v10, v10, v250
	v_mul_f32_e32 v11, v11, v251
	v_lshlrev_b32_e32 v252, 16, v137
	v_and_b32_e32 v253, 0xffff0000, v137
	v_mul_f32_e32 v12, v12, v252
	v_mul_f32_e32 v13, v13, v253
	v_cvt_pk_bf16_f32 v134, v14, v15
	v_cvt_pk_bf16_f32 v135, v16, v17
	v_cvt_pk_bf16_f32 v136, v10, v11
	v_cvt_pk_bf16_f32 v137, v12, v13
	global_store_dwordx4 v[148:149], v[134:137], off
	s_nop 1
	s_waitcnt vmcnt(4)
	v_lshlrev_b32_e32 v250, 16, v234
	v_and_b32_e32 v251, 0xffff0000, v234
	v_mul_f32_e32 v6, v6, v250
	v_mul_f32_e32 v7, v7, v251
	v_lshlrev_b32_e32 v252, 16, v235
	v_and_b32_e32 v253, 0xffff0000, v235
	v_mul_f32_e32 v8, v8, v252
	v_mul_f32_e32 v9, v9, v253
	v_lshlrev_b32_e32 v250, 16, v236
	v_and_b32_e32 v251, 0xffff0000, v236
	v_mul_f32_e32 v2, v2, v250
	v_mul_f32_e32 v3, v3, v251
	v_lshlrev_b32_e32 v252, 16, v237
	v_and_b32_e32 v253, 0xffff0000, v237
	v_mul_f32_e32 v4, v4, v252
	v_mul_f32_e32 v5, v5, v253
	v_cvt_pk_bf16_f32 v234, v6, v7
	v_cvt_pk_bf16_f32 v235, v8, v9
	v_cvt_pk_bf16_f32 v236, v2, v3
	v_cvt_pk_bf16_f32 v237, v4, v5
	global_store_dwordx4 v[148:149], v[234:237], off offset:256
	s_nop 1
	s_mov_b64 s[2:3], -1
	s_andn2_b64 vcc, exec, s[40:41]
	s_cbranch_vccnz .LBB0_204
	s_andn2_b64 vcc, exec, s[10:11]
	s_cbranch_vccnz .LBB0_203
	s_barrier
	s_branch .LBB0_203

;     __device__ __forceinline__ void operator()(const f32x4 (&acc)[2][2][4][2], const Unit& u, int wr, int wc, int fr, int fq) const {
;     ...
; #pragma unroll
;                 for (int m = 0; m < 4; ++m) { const size_t row = rowb + ai * HALF + m * 16; const float r = __builtin_amdgcn_rsqf(ssq_kv[row] * (1.0f / 128.0f) + RMS_EPS);
;                     const size_t hrow = ((((row >> 12) * 8 + head) << 12) + (row & 4095));
;                     if (wc >= 2) {
; #pragma unroll
;                         for (int bj = 0; bj < 2; ++bj) { const f32x4 a = acc[ai][bj][m][0] * r, b = acc[ai][bj][m][1] * r;
;                             u32x4 w; w.x = cvt_pk_bf16(a[0], a[1]); w.y = cvt_pk_bf16(a[2], a[3]); w.z = cvt_pk_bf16(b[0], b[1]); w.w = cvt_pk_bf16(b[2], b[3]);
;                             *(u32x4*)(Vp + hrow * 64 + 32 * bj + 8 * fq) = w; }
;                     } else {
;                         float s = 0.f;
; #pragma unroll
;                         for (int bj = 0; bj < 2; ++bj) { const f32x4 a = acc[ai][bj][m][0], b = acc[ai][bj][m][1]; s += ((a[0] * a[0] + a[1] * a[1]) + (a[2] * a[2] + a[3] * a[3])) + ((b[0] * b[0] + b[1] * b[1]) + (b[2] * b[2] + b[3] * b[3])); }
;                         s += __shfl_xor(s, 16); s += __shfl_xor(s, 32);
;                         const float rh = __builtin_amdgcn_rsqf((s * r * r + ssq_kr[row]) * (1.0f / 96.0f) + RMS_EPS); const float rr = r * rh;
; #pragma unroll
;                         for (int bj = 0; bj < 2; ++bj) { const f32x4 a = acc[ai][bj][m][0] * rr * *(const f32x4*)(kg + 32 * bj + 8 * fq), b = acc[ai][bj][m][1] * rr * *(const f32x4*)(kg + 32 * bj + 8 * fq + 4);
;                             u32x4 w; w.x = cvt_pk_bf16(a[0], a[1]); w.y = cvt_pk_bf16(a[2], a[3]); w.z = cvt_pk_bf16(b[0], b[1]); w.w = cvt_pk_bf16(b[2], b[3]);
;                             *(u32x4*)(Kp + hrow * 96 + 32 * bj + 8 * fq) = w; }
;                         rh8[ai][m] = rh;
;                     }
;                     asm volatile("" ::: "memory"); }
;             if (wc < 2) {
; #pragma unroll
;                 for (int ai = 0; ai < 2; ++ai)
; #pragma unroll
;                     for (int m = 0; m < 4; ++m) { const size_t row = rowb + ai * HALF + m * 16; const size_t hrow = ((((row >> 12) * 8 + head) << 12) + (row & 4095)); const float rh = rh8[ai][m];
.LBB0_488:
	s_ashr_i32 s3, s2, 31
	s_lshl_b64 s[2:3], s[2:3], 8
	s_add_u32 s2, s2, s72
	v_mov_b32_e32 v0, v221
	s_addc_u32 s3, s3, s88
	v_mov_b32_e32 v143, s3
	v_bfe_u32 v167, v0, 4, 2
	v_and_or_b32 v142, v0, 15, s2
	s_cmp_gt_i32 s60, 2
	s_mov_b64 s[34:35], -1
	s_mov_b32 s95, 0xb0000
	s_mov_b64 s[96:97], 0x90
	v_mov_b64_e32 v[226:227], v[224:225]
	v_mov_b32_e32 v224, v220
	s_cbranch_scc0 .LBB0_525
	v_lshl_add_u64 v[148:149], v[142:143], 2, s[16:17]
	flat_load_dword v130, v[148:149]
	s_lshl_b32 s30, s60, 1
	s_lshr_b64 s[2:3], s[2:3], 9
	s_add_i32 s30, s89, s30
	s_and_b32 s3, s3, 0xfffff
	s_and_b32 s2, s2, -8
	s_add_u32 s2, s2, s30
	s_addc_u32 s3, s3, 0
	v_lshlrev_b32_e32 v144, 3, v167
	v_lshlrev_b32_e32 v0, 4, v167
	v_and_b32_e32 v131, 0xfcf, v142
	s_lshl_b64 s[2:3], s[2:3], 12
	v_lshl_add_u64 v[156:157], s[12:13], 0, v[0:1]
	v_mov_b32_e32 v147, s3
	v_or_b32_e32 v146, s2, v131
	s_and_b64 vcc, exec, s[46:47]
	v_lshlrev_b32_e32 v145, 2, v144
	s_cbranch_vccz .Lqkv_orig
	v_mul_u32_u24_e32 v204, 0xc0, v146
	v_add_u32_e32 v204, v204, v0
	v_lshlrev_b32_e32 v205, 10, v142
	v_add_u32_e32 v205, v205, v144
	v_add_u32_e32 v205, 0x8000000, v205
	v_lshlrev_b32_e32 v206, 7, v142
	v_add_u32_e32 v206, v206, v0
	v_lshlrev_b32_e32 v207, 2, v142
	global_load_dword v160, v[148:149], off offset:0
	global_load_dword v161, v[148:149], off offset:64
	global_load_dword v162, v[148:149], off offset:128
	global_load_dword v163, v[148:149], off offset:192
	global_load_dword v164, v[148:149], off offset:512
	global_load_dword v165, v[148:149], off offset:576
	global_load_dword v166, v[148:149], off offset:640
	global_load_dword v167, v[148:149], off offset:704
	global_load_dword v168, v207, s[18:19] offset:0
	global_load_dword v169, v207, s[18:19] offset:64
	global_load_dword v170, v207, s[18:19] offset:128
	global_load_dword v171, v207, s[18:19] offset:192
	global_load_dword v172, v207, s[18:19] offset:512
	global_load_dword v173, v207, s[18:19] offset:576
	global_load_dword v174, v207, s[18:19] offset:640
	global_load_dword v175, v207, s[18:19] offset:704
	global_load_dwordx4 v[176:179], v145, s[8:9] offset:0
	global_load_dwordx4 v[180:183], v145, s[8:9] offset:16
	global_load_dwordx4 v[184:187], v145, s[8:9] offset:128
	global_load_dwordx4 v[188:191], v145, s[8:9] offset:144
	global_load_dwordx4 v[192:195], v0, s[8:9] offset:256
	global_load_dwordx4 v[196:199], v0, s[8:9] offset:320
	s_waitcnt vmcnt(0)
	v_fmamk_f32 v156, v160, 0x3c000000, v231
	v_rsq_f32_e32 v156, v156
	v_pk_mul_f32 v[154:155], v[114:115], v[114:115]
	v_pk_fma_f32 v[154:155], v[116:117], v[116:117], v[154:155]
	v_pk_fma_f32 v[154:155], v[118:119], v[118:119], v[154:155]
	v_pk_fma_f32 v[154:155], v[120:121], v[120:121], v[154:155]
	v_pk_fma_f32 v[154:155], v[122:123], v[122:123], v[154:155]
	v_pk_fma_f32 v[154:155], v[124:125], v[124:125], v[154:155]
	v_pk_fma_f32 v[154:155], v[126:127], v[126:127], v[154:155]
	v_pk_fma_f32 v[154:155], v[128:129], v[128:129], v[154:155]
	v_add_f32_e32 v154, v154, v155
	v_mov_b32_e32 v152, v154
	s_nop 1
	v_permlane16_swap_b32_e32 v154, v152
	v_add_f32_e32 v154, v154, v152
	v_mov_b32_e32 v152, v154
	s_nop 1
	v_permlane32_swap_b32_e32 v154, v152
	v_add_f32_e32 v154, v154, v152
	v_mul_f32_e32 v152, v156, v154
	v_fma_f32 v152, v156, v152, v168
	v_fmamk_f32 v152, v152, 0x3c2aaaab, v231
	v_rsq_f32_e32 v157, v152
	s_nop 0
	v_mul_f32_e32 v150, v156, v157
	v_pk_mul_f32 v[130:131], v[114:115], v[150:151] op_sel_hi:[1,0]
	v_pk_mul_f32 v[130:131], v[176:177], v[130:131]
	v_cvt_pk_bf16_f32 v200, v130, v131
	v_pk_mul_f32 v[132:133], v[116:117], v[150:151] op_sel_hi:[1,0]
	v_pk_mul_f32 v[132:133], v[178:179], v[132:133]
	v_cvt_pk_bf16_f32 v201, v132, v133
	v_pk_mul_f32 v[130:131], v[118:119], v[150:151] op_sel_hi:[1,0]
	v_pk_mul_f32 v[130:131], v[180:181], v[130:131]
	v_cvt_pk_bf16_f32 v202, v130, v131
	v_pk_mul_f32 v[132:133], v[120:121], v[150:151] op_sel_hi:[1,0]
	v_pk_mul_f32 v[132:133], v[182:183], v[132:133]
	v_cvt_pk_bf16_f32 v203, v132, v133
	global_store_dwordx4 v204, v[200:203], s[12:13]
	v_pk_mul_f32 v[130:131], v[122:123], v[150:151] op_sel_hi:[1,0]
	v_pk_mul_f32 v[130:131], v[184:185], v[130:131]
	v_cvt_pk_bf16_f32 v200, v130, v131
	v_pk_mul_f32 v[132:133], v[124:125], v[150:151] op_sel_hi:[1,0]
	v_pk_mul_f32 v[132:133], v[186:187], v[132:133]
	v_cvt_pk_bf16_f32 v201, v132, v133
	v_pk_mul_f32 v[130:131], v[126:127], v[150:151] op_sel_hi:[1,0]
	v_pk_mul_f32 v[130:131], v[188:189], v[130:131]
	v_cvt_pk_bf16_f32 v202, v130, v131
	v_pk_mul_f32 v[132:133], v[128:129], v[150:151] op_sel_hi:[1,0]
	v_pk_mul_f32 v[132:133], v[190:191], v[132:133]
	v_cvt_pk_bf16_f32 v203, v132, v133
	global_store_dwordx4 v204, v[200:203], s[12:13] offset:64
	v_mov_b32_e32 v208, v204
	global_load_dwordx2 v[122:123], v205, s[92:93] offset:768
	global_load_dwordx2 v[124:125], v205, s[92:93] offset:800
	global_load_dwordx4 v[114:117], v206, s[14:15]
	global_load_dwordx4 v[118:121], v206, s[14:15] offset:64
	v_add_u32_e32 v205, 0x4000, v205
	v_add_u32_e32 v206, 0x800, v206
	v_add_u32_e32 v204, 0xc00, v204
	v_fmamk_f32 v156, v161, 0x3c000000, v231
	v_rsq_f32_e32 v156, v156
	v_pk_mul_f32 v[154:155], v[98:99], v[98:99]
	v_pk_fma_f32 v[154:155], v[100:101], v[100:101], v[154:155]
	v_pk_fma_f32 v[154:155], v[102:103], v[102:103], v[154:155]
	v_pk_fma_f32 v[154:155], v[104:105], v[104:105], v[154:155]
	v_pk_fma_f32 v[154:155], v[106:107], v[106:107], v[154:155]
	v_pk_fma_f32 v[154:155], v[108:109], v[108:109], v[154:155]
	v_pk_fma_f32 v[154:155], v[110:111], v[110:111], v[154:155]
	v_pk_fma_f32 v[154:155], v[112:113], v[112:113], v[154:155]
	v_add_f32_e32 v154, v154, v155
	v_mov_b32_e32 v152, v154
	s_nop 1
;     __device__ __forceinline__ void operator()(const f32x4 (&acc)[2][2][4][2], const Unit& u, int wr, int wc, int fr, int fq) const {
;     ...
;                         float s = 0.f;
; #pragma unroll
;                         for (int bj = 0; bj < 2; ++bj) { const f32x4 a = acc[ai][bj][m][0], b = acc[ai][bj][m][1]; s += ((a[0] * a[0] + a[1] * a[1]) + (a[2] * a[2] + a[3] * a[3])) + ((b[0] * b[0] + b[1] * b[1]) + (b[2] * b[2] + b[3] * b[3])); }
;                         s += __shfl_xor(s, 16); s += __shfl_xor(s, 32);
;                         const float rh = __builtin_amdgcn_rsqf((s * r * r + ssq_kr[row]) * (1.0f / 96.0f) + RMS_EPS); const float rr = r * rh;
; #pragma unroll
;                         for (int bj = 0; bj < 2; ++bj) { const f32x4 a = acc[ai][bj][m][0] * rr * *(const f32x4*)(kg + 32 * bj + 8 * fq), b = acc[ai][bj][m][1] * rr * *(const f32x4*)(kg + 32 * bj + 8 * fq + 4);
;                             u32x4 w; w.x = cvt_pk_bf16(a[0], a[1]); w.y = cvt_pk_bf16(a[2], a[3]); w.z = cvt_pk_bf16(b[0], b[1]); w.w = cvt_pk_bf16(b[2], b[3]);
;                             *(u32x4*)(Kp + hrow * 96 + 32 * bj + 8 * fq) = w; }
;                         rh8[ai][m] = rh;
;                     }
;                     asm volatile("" ::: "memory"); }
;             if (wc < 2) {
; #pragma unroll
;                 for (int ai = 0; ai < 2; ++ai)
; #pragma unroll
;                     for (int m = 0; m < 4; ++m) { const size_t row = rowb + ai * HALF + m * 16; const size_t hrow = ((((row >> 12) * 8 + head) << 12) + (row & 4095)); const float rh = rh8[ai][m];
;                         const bf16_t* krp = PA + row * 512 + 384; const float* rp = ROPE + row * 32;
;                         { const int i0 = 4 * fq; const u32x2 xa = *(const u32x2*)(krp + i0), xb = *(const u32x2*)(krp + 16 + i0);
;                             const f32x4 cs = *(const f32x4*)(rp + i0), sn = *(const f32x4*)(rp + 16 + i0), ga = *(const f32x4*)(kg + 64 + i0), gb = *(const f32x4*)(kg + 80 + i0);
;                             const f32x4 a = (f32x4){bf_lo(xa.x), bf_hi(xa.x), bf_lo(xa.y), bf_hi(xa.y)} * rh * ga, bb = (f32x4){bf_lo(xb.x), bf_hi(xb.x), bf_lo(xb.y), bf_hi(xb.y)} * rh * gb;
;                             const f32x4 o1_ = a * cs - bb * sn, o2_ = bb * cs + a * sn;
	v_permlane16_swap_b32_e32 v154, v152
	v_add_f32_e32 v154, v154, v152
	v_mov_b32_e32 v152, v154
	s_nop 1
	v_permlane32_swap_b32_e32 v154, v152
	v_add_f32_e32 v154, v154, v152
	v_mul_f32_e32 v152, v156, v154
	v_fma_f32 v152, v156, v152, v169
	v_fmamk_f32 v152, v152, 0x3c2aaaab, v231
	v_rsq_f32_e32 v158, v152
	s_nop 0
	v_mul_f32_e32 v150, v156, v158
	v_pk_mul_f32 v[130:131], v[98:99], v[150:151] op_sel_hi:[1,0]
	v_pk_mul_f32 v[130:131], v[176:177], v[130:131]
	v_cvt_pk_bf16_f32 v200, v130, v131
	v_pk_mul_f32 v[132:133], v[100:101], v[150:151] op_sel_hi:[1,0]
	v_pk_mul_f32 v[132:133], v[178:179], v[132:133]
	v_cvt_pk_bf16_f32 v201, v132, v133
	v_pk_mul_f32 v[130:131], v[102:103], v[150:151] op_sel_hi:[1,0]
	v_pk_mul_f32 v[130:131], v[180:181], v[130:131]
	v_cvt_pk_bf16_f32 v202, v130, v131
	v_pk_mul_f32 v[132:133], v[104:105], v[150:151] op_sel_hi:[1,0]
	v_pk_mul_f32 v[132:133], v[182:183], v[132:133]
	v_cvt_pk_bf16_f32 v203, v132, v133
	global_store_dwordx4 v204, v[200:203], s[12:13]
	v_pk_mul_f32 v[130:131], v[106:107], v[150:151] op_sel_hi:[1,0]
	v_pk_mul_f32 v[130:131], v[184:185], v[130:131]
	v_cvt_pk_bf16_f32 v200, v130, v131
	v_pk_mul_f32 v[132:133], v[108:109], v[150:151] op_sel_hi:[1,0]
	v_pk_mul_f32 v[132:133], v[186:187], v[132:133]
	v_cvt_pk_bf16_f32 v201, v132, v133
	v_pk_mul_f32 v[130:131], v[110:111], v[150:151] op_sel_hi:[1,0]
	v_pk_mul_f32 v[130:131], v[188:189], v[130:131]
	v_cvt_pk_bf16_f32 v202, v130, v131
	v_pk_mul_f32 v[132:133], v[112:113], v[150:151] op_sel_hi:[1,0]
	v_pk_mul_f32 v[132:133], v[190:191], v[132:133]
	v_cvt_pk_bf16_f32 v203, v132, v133
	global_store_dwordx4 v204, v[200:203], s[12:13] offset:64
	s_waitcnt vmcnt(2)
	v_lshlrev_b32_e32 v126, 16, v122
	v_and_b32_e32 v127, 0xffff0000, v122
	v_lshlrev_b32_e32 v128, 16, v123
	v_and_b32_e32 v129, 0xffff0000, v123
	v_lshlrev_b32_e32 v130, 16, v124
	v_and_b32_e32 v131, 0xffff0000, v124
	v_lshlrev_b32_e32 v132, 16, v125
	v_and_b32_e32 v133, 0xffff0000, v125
	v_mov_b32_e32 v150, v157
	v_pk_mul_f32 v[126:127], v[126:127], v[150:151] op_sel_hi:[1,0]
	v_pk_mul_f32 v[128:129], v[128:129], v[150:151] op_sel_hi:[1,0]
	v_pk_mul_f32 v[130:131], v[130:131], v[150:151] op_sel_hi:[1,0]
	v_pk_mul_f32 v[132:133], v[132:133], v[150:151] op_sel_hi:[1,0]
	v_pk_mul_f32 v[126:127], v[192:193], v[126:127]
	v_pk_mul_f32 v[128:129], v[194:195], v[128:129]
	v_pk_mul_f32 v[130:131], v[196:197], v[130:131]
	v_pk_mul_f32 v[132:133], v[198:199], v[132:133]
	v_pk_mul_f32 v[122:123], v[118:119], v[130:131]
	v_pk_fma_f32 v[122:123], v[114:115], v[126:127], v[122:123] neg_lo:[0,0,1] neg_hi:[0,0,1]
	v_pk_mul_f32 v[124:125], v[120:121], v[132:133]
	v_pk_fma_f32 v[124:125], v[116:117], v[128:129], v[124:125] neg_lo:[0,0,1] neg_hi:[0,0,1]
	v_pk_mul_f32 v[130:131], v[114:115], v[130:131]
	v_pk_fma_f32 v[130:131], v[118:119], v[126:127], v[130:131]
	v_pk_mul_f32 v[132:133], v[116:117], v[132:133]
	v_pk_fma_f32 v[132:133], v[120:121], v[128:129], v[132:133]
	v_cvt_pk_bf16_f32 v126, v122, v123
	v_cvt_pk_bf16_f32 v127, v124, v125
	v_cvt_pk_bf16_f32 v128, v130, v131
	v_cvt_pk_bf16_f32 v129, v132, v133
	v_sub_u32_e32 v152, v208, v144
	global_store_dwordx2 v152, v[126:127], s[12:13] offset:128
	global_store_dwordx2 v152, v[128:129], s[12:13] offset:160
	v_mov_b32_e32 v208, v204
	global_load_dwordx2 v[106:107], v205, s[92:93] offset:768
	global_load_dwordx2 v[108:109], v205, s[92:93] offset:800
	global_load_dwordx4 v[98:101], v206, s[14:15]
	global_load_dwordx4 v[102:105], v206, s[14:15] offset:64
	v_add_u32_e32 v205, 0x4000, v205
	v_add_u32_e32 v206, 0x800, v206
	v_add_u32_e32 v204, 0xc00, v204
	v_fmamk_f32 v156, v162, 0x3c000000, v231
	v_rsq_f32_e32 v156, v156
	v_pk_mul_f32 v[154:155], v[82:83], v[82:83]
	v_pk_fma_f32 v[154:155], v[84:85], v[84:85], v[154:155]
	v_pk_fma_f32 v[154:155], v[86:87], v[86:87], v[154:155]
	v_pk_fma_f32 v[154:155], v[88:89], v[88:89], v[154:155]
	v_pk_fma_f32 v[154:155], v[90:91], v[90:91], v[154:155]
	v_pk_fma_f32 v[154:155], v[92:93], v[92:93], v[154:155]
	v_pk_fma_f32 v[154:155], v[94:95], v[94:95], v[154:155]
	v_pk_fma_f32 v[154:155], v[96:97], v[96:97], v[154:155]
	v_add_f32_e32 v154, v154, v155
	v_mov_b32_e32 v152, v154
	s_nop 1
	v_permlane16_swap_b32_e32 v154, v152
	v_add_f32_e32 v154, v154, v152
	v_mov_b32_e32 v152, v154
	s_nop 1
	v_permlane32_swap_b32_e32 v154, v152
	v_add_f32_e32 v154, v154, v152
	v_mul_f32_e32 v152, v156, v154
	v_fma_f32 v152, v156, v152, v170
	v_fmamk_f32 v152, v152, 0x3c2aaaab, v231
	v_rsq_f32_e32 v157, v152
	s_nop 0
	v_mul_f32_e32 v150, v156, v157
	v_pk_mul_f32 v[130:131], v[82:83], v[150:151] op_sel_hi:[1,0]
	v_pk_mul_f32 v[130:131], v[176:177], v[130:131]
	v_cvt_pk_bf16_f32 v200, v130, v131
	v_pk_mul_f32 v[132:133], v[84:85], v[150:151] op_sel_hi:[1,0]
	v_pk_mul_f32 v[132:133], v[178:179], v[132:133]
	v_cvt_pk_bf16_f32 v201, v132, v133
	v_pk_mul_f32 v[130:131], v[86:87], v[150:151] op_sel_hi:[1,0]
	v_pk_mul_f32 v[130:131], v[180:181], v[130:131]
	v_cvt_pk_bf16_f32 v202, v130, v131
	v_pk_mul_f32 v[132:133], v[88:89], v[150:151] op_sel_hi:[1,0]
	v_pk_mul_f32 v[132:133], v[182:183], v[132:133]
	v_cvt_pk_bf16_f32 v203, v132, v133
	global_store_dwordx4 v204, v[200:203], s[12:13]
	v_pk_mul_f32 v[130:131], v[90:91], v[150:151] op_sel_hi:[1,0]
	v_pk_mul_f32 v[130:131], v[184:185], v[130:131]
	v_cvt_pk_bf16_f32 v200, v130, v131
	v_pk_mul_f32 v[132:133], v[92:93], v[150:151] op_sel_hi:[1,0]
	v_pk_mul_f32 v[132:133], v[186:187], v[132:133]
	v_cvt_pk_bf16_f32 v201, v132, v133
	v_pk_mul_f32 v[130:131], v[94:95], v[150:151] op_sel_hi:[1,0]
	v_pk_mul_f32 v[130:131], v[188:189], v[130:131]
	v_cvt_pk_bf16_f32 v202, v130, v131
	v_pk_mul_f32 v[132:133], v[96:97], v[150:151] op_sel_hi:[1,0]
	v_pk_mul_f32 v[132:133], v[190:191], v[132:133]
	v_cvt_pk_bf16_f32 v203, v132, v133
	global_store_dwordx4 v204, v[200:203], s[12:13] offset:64
	s_waitcnt vmcnt(2)
;     __device__ __forceinline__ void operator()(const f32x4 (&acc)[2][2][4][2], const Unit& u, int wr, int wc, int fr, int fq) const {
;     ...
;                         float s = 0.f;
; #pragma unroll
;                         for (int bj = 0; bj < 2; ++bj) { const f32x4 a = acc[ai][bj][m][0], b = acc[ai][bj][m][1]; s += ((a[0] * a[0] + a[1] * a[1]) + (a[2] * a[2] + a[3] * a[3])) + ((b[0] * b[0] + b[1] * b[1]) + (b[2] * b[2] + b[3] * b[3])); }
;                         s += __shfl_xor(s, 16); s += __shfl_xor(s, 32);
;                         const float rh = __builtin_amdgcn_rsqf((s * r * r + ssq_kr[row]) * (1.0f / 96.0f) + RMS_EPS); const float rr = r * rh;
; #pragma unroll
;                         for (int bj = 0; bj < 2; ++bj) { const f32x4 a = acc[ai][bj][m][0] * rr * *(const f32x4*)(kg + 32 * bj + 8 * fq), b = acc[ai][bj][m][1] * rr * *(const f32x4*)(kg + 32 * bj + 8 * fq + 4);
;                             u32x4 w; w.x = cvt_pk_bf16(a[0], a[1]); w.y = cvt_pk_bf16(a[2], a[3]); w.z = cvt_pk_bf16(b[0], b[1]); w.w = cvt_pk_bf16(b[2], b[3]);
;                             *(u32x4*)(Kp + hrow * 96 + 32 * bj + 8 * fq) = w; }
;                         rh8[ai][m] = rh;
;                     }
;                     asm volatile("" ::: "memory"); }
;             if (wc < 2) {
; #pragma unroll
;                 for (int ai = 0; ai < 2; ++ai)
; #pragma unroll
;                     for (int m = 0; m < 4; ++m) { const size_t row = rowb + ai * HALF + m * 16; const size_t hrow = ((((row >> 12) * 8 + head) << 12) + (row & 4095)); const float rh = rh8[ai][m];
;                         const bf16_t* krp = PA + row * 512 + 384; const float* rp = ROPE + row * 32;
;                         { const int i0 = 4 * fq; const u32x2 xa = *(const u32x2*)(krp + i0), xb = *(const u32x2*)(krp + 16 + i0);
;                             const f32x4 cs = *(const f32x4*)(rp + i0), sn = *(const f32x4*)(rp + 16 + i0), ga = *(const f32x4*)(kg + 64 + i0), gb = *(const f32x4*)(kg + 80 + i0);
;                             const f32x4 a = (f32x4){bf_lo(xa.x), bf_hi(xa.x), bf_lo(xa.y), bf_hi(xa.y)} * rh * ga, bb = (f32x4){bf_lo(xb.x), bf_hi(xb.x), bf_lo(xb.y), bf_hi(xb.y)} * rh * gb;
;                             const f32x4 o1_ = a * cs - bb * sn, o2_ = bb * cs + a * sn;
	v_lshlrev_b32_e32 v110, 16, v106
	v_and_b32_e32 v111, 0xffff0000, v106
	v_lshlrev_b32_e32 v112, 16, v107
	v_and_b32_e32 v113, 0xffff0000, v107
	v_lshlrev_b32_e32 v130, 16, v108
	v_and_b32_e32 v131, 0xffff0000, v108
	v_lshlrev_b32_e32 v132, 16, v109
	v_and_b32_e32 v133, 0xffff0000, v109
	v_mov_b32_e32 v150, v158
	v_pk_mul_f32 v[110:111], v[110:111], v[150:151] op_sel_hi:[1,0]
	v_pk_mul_f32 v[112:113], v[112:113], v[150:151] op_sel_hi:[1,0]
	v_pk_mul_f32 v[130:131], v[130:131], v[150:151] op_sel_hi:[1,0]
	v_pk_mul_f32 v[132:133], v[132:133], v[150:151] op_sel_hi:[1,0]
	v_pk_mul_f32 v[110:111], v[192:193], v[110:111]
	v_pk_mul_f32 v[112:113], v[194:195], v[112:113]
	v_pk_mul_f32 v[130:131], v[196:197], v[130:131]
	v_pk_mul_f32 v[132:133], v[198:199], v[132:133]
	v_pk_mul_f32 v[106:107], v[102:103], v[130:131]
	v_pk_fma_f32 v[106:107], v[98:99], v[110:111], v[106:107] neg_lo:[0,0,1] neg_hi:[0,0,1]
	v_pk_mul_f32 v[108:109], v[104:105], v[132:133]
	v_pk_fma_f32 v[108:109], v[100:101], v[112:113], v[108:109] neg_lo:[0,0,1] neg_hi:[0,0,1]
	v_pk_mul_f32 v[130:131], v[98:99], v[130:131]
	v_pk_fma_f32 v[130:131], v[102:103], v[110:111], v[130:131]
	v_pk_mul_f32 v[132:133], v[100:101], v[132:133]
	v_pk_fma_f32 v[132:133], v[104:105], v[112:113], v[132:133]
	v_cvt_pk_bf16_f32 v110, v106, v107
	v_cvt_pk_bf16_f32 v111, v108, v109
	v_cvt_pk_bf16_f32 v112, v130, v131
	v_cvt_pk_bf16_f32 v113, v132, v133
	v_sub_u32_e32 v152, v208, v144
	global_store_dwordx2 v152, v[110:111], s[12:13] offset:128
	global_store_dwordx2 v152, v[112:113], s[12:13] offset:160
	v_mov_b32_e32 v208, v204
	global_load_dwordx2 v[90:91], v205, s[92:93] offset:768
	global_load_dwordx2 v[92:93], v205, s[92:93] offset:800
	global_load_dwordx4 v[82:85], v206, s[14:15]
	global_load_dwordx4 v[86:89], v206, s[14:15] offset:64
	v_add_u32_e32 v205, 0x4000, v205
	v_add_u32_e32 v206, 0x800, v206
	v_add_u32_e32 v204, 0xc00, v204
	v_fmamk_f32 v156, v163, 0x3c000000, v231
	v_rsq_f32_e32 v156, v156
	v_pk_mul_f32 v[154:155], v[74:75], v[74:75]
	v_pk_fma_f32 v[154:155], v[76:77], v[76:77], v[154:155]
	v_pk_fma_f32 v[154:155], v[78:79], v[78:79], v[154:155]
	v_pk_fma_f32 v[154:155], v[80:81], v[80:81], v[154:155]
	v_pk_fma_f32 v[154:155], v[70:71], v[70:71], v[154:155]
	v_pk_fma_f32 v[154:155], v[72:73], v[72:73], v[154:155]
	v_pk_fma_f32 v[154:155], v[66:67], v[66:67], v[154:155]
	v_pk_fma_f32 v[154:155], v[68:69], v[68:69], v[154:155]
	v_add_f32_e32 v154, v154, v155
	v_mov_b32_e32 v152, v154
	s_nop 1
	v_permlane16_swap_b32_e32 v154, v152
	v_add_f32_e32 v154, v154, v152
	v_mov_b32_e32 v152, v154
	s_nop 1
	v_permlane32_swap_b32_e32 v154, v152
	v_add_f32_e32 v154, v154, v152
	v_mul_f32_e32 v152, v156, v154
	v_fma_f32 v152, v156, v152, v171
	v_fmamk_f32 v152, v152, 0x3c2aaaab, v231
	v_rsq_f32_e32 v158, v152
	s_nop 0
	v_mul_f32_e32 v150, v156, v158
	v_pk_mul_f32 v[130:131], v[74:75], v[150:151] op_sel_hi:[1,0]
	v_pk_mul_f32 v[130:131], v[176:177], v[130:131]
	v_cvt_pk_bf16_f32 v200, v130, v131
	v_pk_mul_f32 v[132:133], v[76:77], v[150:151] op_sel_hi:[1,0]
	v_pk_mul_f32 v[132:133], v[178:179], v[132:133]
	v_cvt_pk_bf16_f32 v201, v132, v133
	v_pk_mul_f32 v[130:131], v[78:79], v[150:151] op_sel_hi:[1,0]
	v_pk_mul_f32 v[130:131], v[180:181], v[130:131]
	v_cvt_pk_bf16_f32 v202, v130, v131
	v_pk_mul_f32 v[132:133], v[80:81], v[150:151] op_sel_hi:[1,0]
	v_pk_mul_f32 v[132:133], v[182:183], v[132:133]
	v_cvt_pk_bf16_f32 v203, v132, v133
	global_store_dwordx4 v204, v[200:203], s[12:13]
	v_pk_mul_f32 v[130:131], v[70:71], v[150:151] op_sel_hi:[1,0]
	v_pk_mul_f32 v[130:131], v[184:185], v[130:131]
	v_cvt_pk_bf16_f32 v200, v130, v131
	v_pk_mul_f32 v[132:133], v[72:73], v[150:151] op_sel_hi:[1,0]
	v_pk_mul_f32 v[132:133], v[186:187], v[132:133]
	v_cvt_pk_bf16_f32 v201, v132, v133
	v_pk_mul_f32 v[130:131], v[66:67], v[150:151] op_sel_hi:[1,0]
	v_pk_mul_f32 v[130:131], v[188:189], v[130:131]
	v_cvt_pk_bf16_f32 v202, v130, v131
	v_pk_mul_f32 v[132:133], v[68:69], v[150:151] op_sel_hi:[1,0]
	v_pk_mul_f32 v[132:133], v[190:191], v[132:133]
	v_cvt_pk_bf16_f32 v203, v132, v133
	global_store_dwordx4 v204, v[200:203], s[12:13] offset:64
	s_waitcnt vmcnt(2)
	v_lshlrev_b32_e32 v94, 16, v90
	v_and_b32_e32 v95, 0xffff0000, v90
	v_lshlrev_b32_e32 v96, 16, v91
	v_and_b32_e32 v97, 0xffff0000, v91
	v_lshlrev_b32_e32 v130, 16, v92
	v_and_b32_e32 v131, 0xffff0000, v92
	v_lshlrev_b32_e32 v132, 16, v93
	v_and_b32_e32 v133, 0xffff0000, v93
	v_mov_b32_e32 v150, v157
	v_pk_mul_f32 v[94:95], v[94:95], v[150:151] op_sel_hi:[1,0]
	v_pk_mul_f32 v[96:97], v[96:97], v[150:151] op_sel_hi:[1,0]
	v_pk_mul_f32 v[130:131], v[130:131], v[150:151] op_sel_hi:[1,0]
	v_pk_mul_f32 v[132:133], v[132:133], v[150:151] op_sel_hi:[1,0]
	v_pk_mul_f32 v[94:95], v[192:193], v[94:95]
	v_pk_mul_f32 v[96:97], v[194:195], v[96:97]
	v_pk_mul_f32 v[130:131], v[196:197], v[130:131]
	v_pk_mul_f32 v[132:133], v[198:199], v[132:133]
	v_pk_mul_f32 v[90:91], v[86:87], v[130:131]
	v_pk_fma_f32 v[90:91], v[82:83], v[94:95], v[90:91] neg_lo:[0,0,1] neg_hi:[0,0,1]
	v_pk_mul_f32 v[92:93], v[88:89], v[132:133]
	v_pk_fma_f32 v[92:93], v[84:85], v[96:97], v[92:93] neg_lo:[0,0,1] neg_hi:[0,0,1]
	v_pk_mul_f32 v[130:131], v[82:83], v[130:131]
	v_pk_fma_f32 v[130:131], v[86:87], v[94:95], v[130:131]
	v_pk_mul_f32 v[132:133], v[84:85], v[132:133]
	v_pk_fma_f32 v[132:133], v[88:89], v[96:97], v[132:133]
	v_cvt_pk_bf16_f32 v94, v90, v91
	v_cvt_pk_bf16_f32 v95, v92, v93
	v_cvt_pk_bf16_f32 v96, v130, v131
	v_cvt_pk_bf16_f32 v97, v132, v133
	v_sub_u32_e32 v152, v208, v144
	global_store_dwordx2 v152, v[94:95], s[12:13] offset:128
	global_store_dwordx2 v152, v[96:97], s[12:13] offset:160
;     __device__ __forceinline__ void operator()(const f32x4 (&acc)[2][2][4][2], const Unit& u, int wr, int wc, int fr, int fq) const {
;     ...
;                         float s = 0.f;
; #pragma unroll
;                         for (int bj = 0; bj < 2; ++bj) { const f32x4 a = acc[ai][bj][m][0], b = acc[ai][bj][m][1]; s += ((a[0] * a[0] + a[1] * a[1]) + (a[2] * a[2] + a[3] * a[3])) + ((b[0] * b[0] + b[1] * b[1]) + (b[2] * b[2] + b[3] * b[3])); }
;                         s += __shfl_xor(s, 16); s += __shfl_xor(s, 32);
;                         const float rh = __builtin_amdgcn_rsqf((s * r * r + ssq_kr[row]) * (1.0f / 96.0f) + RMS_EPS); const float rr = r * rh;
; #pragma unroll
;                         for (int bj = 0; bj < 2; ++bj) { const f32x4 a = acc[ai][bj][m][0] * rr * *(const f32x4*)(kg + 32 * bj + 8 * fq), b = acc[ai][bj][m][1] * rr * *(const f32x4*)(kg + 32 * bj + 8 * fq + 4);
;                             u32x4 w; w.x = cvt_pk_bf16(a[0], a[1]); w.y = cvt_pk_bf16(a[2], a[3]); w.z = cvt_pk_bf16(b[0], b[1]); w.w = cvt_pk_bf16(b[2], b[3]);
;                             *(u32x4*)(Kp + hrow * 96 + 32 * bj + 8 * fq) = w; }
;                         rh8[ai][m] = rh;
;                     }
;                     asm volatile("" ::: "memory"); }
;             if (wc < 2) {
; #pragma unroll
;                 for (int ai = 0; ai < 2; ++ai)
; #pragma unroll
;                     for (int m = 0; m < 4; ++m) { const size_t row = rowb + ai * HALF + m * 16; const size_t hrow = ((((row >> 12) * 8 + head) << 12) + (row & 4095)); const float rh = rh8[ai][m];
;                         const bf16_t* krp = PA + row * 512 + 384; const float* rp = ROPE + row * 32;
;                         { const int i0 = 4 * fq; const u32x2 xa = *(const u32x2*)(krp + i0), xb = *(const u32x2*)(krp + 16 + i0);
;                             const f32x4 cs = *(const f32x4*)(rp + i0), sn = *(const f32x4*)(rp + 16 + i0), ga = *(const f32x4*)(kg + 64 + i0), gb = *(const f32x4*)(kg + 80 + i0);
;                             const f32x4 a = (f32x4){bf_lo(xa.x), bf_hi(xa.x), bf_lo(xa.y), bf_hi(xa.y)} * rh * ga, bb = (f32x4){bf_lo(xb.x), bf_hi(xb.x), bf_lo(xb.y), bf_hi(xb.y)} * rh * gb;
;                             const f32x4 o1_ = a * cs - bb * sn, o2_ = bb * cs + a * sn;
	v_mov_b32_e32 v208, v204
	global_load_dwordx2 v[74:75], v205, s[92:93] offset:768
	global_load_dwordx2 v[76:77], v205, s[92:93] offset:800
	global_load_dwordx4 v[66:69], v206, s[14:15]
	global_load_dwordx4 v[70:73], v206, s[14:15] offset:64
	v_add_u32_e32 v205, 0x14000, v205
	v_add_u32_e32 v206, 0x2800, v206
	v_add_u32_e32 v204, 0x3c00, v204
	v_fmamk_f32 v156, v164, 0x3c000000, v231
	v_rsq_f32_e32 v156, v156
	v_pk_mul_f32 v[154:155], v[58:59], v[58:59]
	v_pk_fma_f32 v[154:155], v[60:61], v[60:61], v[154:155]
	v_pk_fma_f32 v[154:155], v[62:63], v[62:63], v[154:155]
	v_pk_fma_f32 v[154:155], v[64:65], v[64:65], v[154:155]
	v_pk_fma_f32 v[154:155], v[54:55], v[54:55], v[154:155]
	v_pk_fma_f32 v[154:155], v[56:57], v[56:57], v[154:155]
	v_pk_fma_f32 v[154:155], v[50:51], v[50:51], v[154:155]
	v_pk_fma_f32 v[154:155], v[52:53], v[52:53], v[154:155]
	v_add_f32_e32 v154, v154, v155
	v_mov_b32_e32 v152, v154
	s_nop 1
	v_permlane16_swap_b32_e32 v154, v152
	v_add_f32_e32 v154, v154, v152
	v_mov_b32_e32 v152, v154
	s_nop 1
	v_permlane32_swap_b32_e32 v154, v152
	v_add_f32_e32 v154, v154, v152
	v_mul_f32_e32 v152, v156, v154
	v_fma_f32 v152, v156, v152, v172
	v_fmamk_f32 v152, v152, 0x3c2aaaab, v231
	v_rsq_f32_e32 v157, v152
	s_nop 0
	v_mul_f32_e32 v150, v156, v157
	v_pk_mul_f32 v[130:131], v[58:59], v[150:151] op_sel_hi:[1,0]
	v_pk_mul_f32 v[130:131], v[176:177], v[130:131]
	v_cvt_pk_bf16_f32 v200, v130, v131
	v_pk_mul_f32 v[132:133], v[60:61], v[150:151] op_sel_hi:[1,0]
	v_pk_mul_f32 v[132:133], v[178:179], v[132:133]
	v_cvt_pk_bf16_f32 v201, v132, v133
	v_pk_mul_f32 v[130:131], v[62:63], v[150:151] op_sel_hi:[1,0]
	v_pk_mul_f32 v[130:131], v[180:181], v[130:131]
	v_cvt_pk_bf16_f32 v202, v130, v131
	v_pk_mul_f32 v[132:133], v[64:65], v[150:151] op_sel_hi:[1,0]
	v_pk_mul_f32 v[132:133], v[182:183], v[132:133]
	v_cvt_pk_bf16_f32 v203, v132, v133
	global_store_dwordx4 v204, v[200:203], s[12:13]
	v_pk_mul_f32 v[130:131], v[54:55], v[150:151] op_sel_hi:[1,0]
	v_pk_mul_f32 v[130:131], v[184:185], v[130:131]
	v_cvt_pk_bf16_f32 v200, v130, v131
	v_pk_mul_f32 v[132:133], v[56:57], v[150:151] op_sel_hi:[1,0]
	v_pk_mul_f32 v[132:133], v[186:187], v[132:133]
	v_cvt_pk_bf16_f32 v201, v132, v133
	v_pk_mul_f32 v[130:131], v[50:51], v[150:151] op_sel_hi:[1,0]
	v_pk_mul_f32 v[130:131], v[188:189], v[130:131]
	v_cvt_pk_bf16_f32 v202, v130, v131
	v_pk_mul_f32 v[132:133], v[52:53], v[150:151] op_sel_hi:[1,0]
	v_pk_mul_f32 v[132:133], v[190:191], v[132:133]
	v_cvt_pk_bf16_f32 v203, v132, v133
	global_store_dwordx4 v204, v[200:203], s[12:13] offset:64
	s_waitcnt vmcnt(2)
	v_lshlrev_b32_e32 v78, 16, v74
	v_and_b32_e32 v79, 0xffff0000, v74
	v_lshlrev_b32_e32 v80, 16, v75
	v_and_b32_e32 v81, 0xffff0000, v75
	v_lshlrev_b32_e32 v130, 16, v76
	v_and_b32_e32 v131, 0xffff0000, v76
	v_lshlrev_b32_e32 v132, 16, v77
	v_and_b32_e32 v133, 0xffff0000, v77
	v_mov_b32_e32 v150, v158
	v_pk_mul_f32 v[78:79], v[78:79], v[150:151] op_sel_hi:[1,0]
	v_pk_mul_f32 v[80:81], v[80:81], v[150:151] op_sel_hi:[1,0]
	v_pk_mul_f32 v[130:131], v[130:131], v[150:151] op_sel_hi:[1,0]
	v_pk_mul_f32 v[132:133], v[132:133], v[150:151] op_sel_hi:[1,0]
	v_pk_mul_f32 v[78:79], v[192:193], v[78:79]
	v_pk_mul_f32 v[80:81], v[194:195], v[80:81]
	v_pk_mul_f32 v[130:131], v[196:197], v[130:131]
	v_pk_mul_f32 v[132:133], v[198:199], v[132:133]
	v_pk_mul_f32 v[74:75], v[70:71], v[130:131]
	v_pk_fma_f32 v[74:75], v[66:67], v[78:79], v[74:75] neg_lo:[0,0,1] neg_hi:[0,0,1]
	v_pk_mul_f32 v[76:77], v[72:73], v[132:133]
	v_pk_fma_f32 v[76:77], v[68:69], v[80:81], v[76:77] neg_lo:[0,0,1] neg_hi:[0,0,1]
	v_pk_mul_f32 v[130:131], v[66:67], v[130:131]
	v_pk_fma_f32 v[130:131], v[70:71], v[78:79], v[130:131]
	v_pk_mul_f32 v[132:133], v[68:69], v[132:133]
	v_pk_fma_f32 v[132:133], v[72:73], v[80:81], v[132:133]
	v_cvt_pk_bf16_f32 v78, v74, v75
	v_cvt_pk_bf16_f32 v79, v76, v77
	v_cvt_pk_bf16_f32 v80, v130, v131
	v_cvt_pk_bf16_f32 v81, v132, v133
	v_sub_u32_e32 v152, v208, v144
	global_store_dwordx2 v152, v[78:79], s[12:13] offset:128
	global_store_dwordx2 v152, v[80:81], s[12:13] offset:160
	v_mov_b32_e32 v208, v204
	global_load_dwordx2 v[58:59], v205, s[92:93] offset:768
	global_load_dwordx2 v[60:61], v205, s[92:93] offset:800
	global_load_dwordx4 v[50:53], v206, s[14:15]
	global_load_dwordx4 v[54:57], v206, s[14:15] offset:64
	v_add_u32_e32 v205, 0x4000, v205
	v_add_u32_e32 v206, 0x800, v206
	v_add_u32_e32 v204, 0xc00, v204
	v_fmamk_f32 v156, v165, 0x3c000000, v231
	v_rsq_f32_e32 v156, v156
	v_pk_mul_f32 v[154:155], v[42:43], v[42:43]
	v_pk_fma_f32 v[154:155], v[44:45], v[44:45], v[154:155]
	v_pk_fma_f32 v[154:155], v[46:47], v[46:47], v[154:155]
	v_pk_fma_f32 v[154:155], v[48:49], v[48:49], v[154:155]
	v_pk_fma_f32 v[154:155], v[38:39], v[38:39], v[154:155]
	v_pk_fma_f32 v[154:155], v[40:41], v[40:41], v[154:155]
	v_pk_fma_f32 v[154:155], v[34:35], v[34:35], v[154:155]
	v_pk_fma_f32 v[154:155], v[36:37], v[36:37], v[154:155]
	v_add_f32_e32 v154, v154, v155
	v_mov_b32_e32 v152, v154
	s_nop 1
	v_permlane16_swap_b32_e32 v154, v152
	v_add_f32_e32 v154, v154, v152
	v_mov_b32_e32 v152, v154
	s_nop 1
	v_permlane32_swap_b32_e32 v154, v152
	v_add_f32_e32 v154, v154, v152
	v_mul_f32_e32 v152, v156, v154
	v_fma_f32 v152, v156, v152, v173
	v_fmamk_f32 v152, v152, 0x3c2aaaab, v231
	v_rsq_f32_e32 v158, v152
	s_nop 0
	v_mul_f32_e32 v150, v156, v158
	v_pk_mul_f32 v[130:131], v[42:43], v[150:151] op_sel_hi:[1,0]
	v_pk_mul_f32 v[130:131], v[176:177], v[130:131]
	v_cvt_pk_bf16_f32 v200, v130, v131
	v_pk_mul_f32 v[132:133], v[44:45], v[150:151] op_sel_hi:[1,0]
	v_pk_mul_f32 v[132:133], v[178:179], v[132:133]
	v_cvt_pk_bf16_f32 v201, v132, v133
	v_pk_mul_f32 v[130:131], v[46:47], v[150:151] op_sel_hi:[1,0]
	v_pk_mul_f32 v[130:131], v[180:181], v[130:131]
	v_cvt_pk_bf16_f32 v202, v130, v131
	v_pk_mul_f32 v[132:133], v[48:49], v[150:151] op_sel_hi:[1,0]
	v_pk_mul_f32 v[132:133], v[182:183], v[132:133]
	v_cvt_pk_bf16_f32 v203, v132, v133
	global_store_dwordx4 v204, v[200:203], s[12:13]
	v_pk_mul_f32 v[130:131], v[38:39], v[150:151] op_sel_hi:[1,0]
	v_pk_mul_f32 v[130:131], v[184:185], v[130:131]
	v_cvt_pk_bf16_f32 v200, v130, v131
	v_pk_mul_f32 v[132:133], v[40:41], v[150:151] op_sel_hi:[1,0]
	v_pk_mul_f32 v[132:133], v[186:187], v[132:133]
	v_cvt_pk_bf16_f32 v201, v132, v133
	v_pk_mul_f32 v[130:131], v[34:35], v[150:151] op_sel_hi:[1,0]
	v_pk_mul_f32 v[130:131], v[188:189], v[130:131]
	v_cvt_pk_bf16_f32 v202, v130, v131
	v_pk_mul_f32 v[132:133], v[36:37], v[150:151] op_sel_hi:[1,0]
	v_pk_mul_f32 v[132:133], v[190:191], v[132:133]
	v_cvt_pk_bf16_f32 v203, v132, v133
	global_store_dwordx4 v204, v[200:203], s[12:13] offset:64
	s_waitcnt vmcnt(2)
;     __device__ __forceinline__ void operator()(const f32x4 (&acc)[2][2][4][2], const Unit& u, int wr, int wc, int fr, int fq) const {
;     ...
;                         float s = 0.f;
; #pragma unroll
;                         for (int bj = 0; bj < 2; ++bj) { const f32x4 a = acc[ai][bj][m][0], b = acc[ai][bj][m][1]; s += ((a[0] * a[0] + a[1] * a[1]) + (a[2] * a[2] + a[3] * a[3])) + ((b[0] * b[0] + b[1] * b[1]) + (b[2] * b[2] + b[3] * b[3])); }
;                         s += __shfl_xor(s, 16); s += __shfl_xor(s, 32);
;                         const float rh = __builtin_amdgcn_rsqf((s * r * r + ssq_kr[row]) * (1.0f / 96.0f) + RMS_EPS); const float rr = r * rh;
; #pragma unroll
;                         for (int bj = 0; bj < 2; ++bj) { const f32x4 a = acc[ai][bj][m][0] * rr * *(const f32x4*)(kg + 32 * bj + 8 * fq), b = acc[ai][bj][m][1] * rr * *(const f32x4*)(kg + 32 * bj + 8 * fq + 4);
;                             u32x4 w; w.x = cvt_pk_bf16(a[0], a[1]); w.y = cvt_pk_bf16(a[2], a[3]); w.z = cvt_pk_bf16(b[0], b[1]); w.w = cvt_pk_bf16(b[2], b[3]);
;                             *(u32x4*)(Kp + hrow * 96 + 32 * bj + 8 * fq) = w; }
;                         rh8[ai][m] = rh;
;                     }
;                     asm volatile("" ::: "memory"); }
;             if (wc < 2) {
; #pragma unroll
;                 for (int ai = 0; ai < 2; ++ai)
; #pragma unroll
;                     for (int m = 0; m < 4; ++m) { const size_t row = rowb + ai * HALF + m * 16; const size_t hrow = ((((row >> 12) * 8 + head) << 12) + (row & 4095)); const float rh = rh8[ai][m];
;                         const bf16_t* krp = PA + row * 512 + 384; const float* rp = ROPE + row * 32;
;                         { const int i0 = 4 * fq; const u32x2 xa = *(const u32x2*)(krp + i0), xb = *(const u32x2*)(krp + 16 + i0);
;                             const f32x4 cs = *(const f32x4*)(rp + i0), sn = *(const f32x4*)(rp + 16 + i0), ga = *(const f32x4*)(kg + 64 + i0), gb = *(const f32x4*)(kg + 80 + i0);
;                             const f32x4 a = (f32x4){bf_lo(xa.x), bf_hi(xa.x), bf_lo(xa.y), bf_hi(xa.y)} * rh * ga, bb = (f32x4){bf_lo(xb.x), bf_hi(xb.x), bf_lo(xb.y), bf_hi(xb.y)} * rh * gb;
;                             const f32x4 o1_ = a * cs - bb * sn, o2_ = bb * cs + a * sn;
	v_lshlrev_b32_e32 v62, 16, v58
	v_and_b32_e32 v63, 0xffff0000, v58
	v_lshlrev_b32_e32 v64, 16, v59
	v_and_b32_e32 v65, 0xffff0000, v59
	v_lshlrev_b32_e32 v130, 16, v60
	v_and_b32_e32 v131, 0xffff0000, v60
	v_lshlrev_b32_e32 v132, 16, v61
	v_and_b32_e32 v133, 0xffff0000, v61
	v_mov_b32_e32 v150, v157
	v_pk_mul_f32 v[62:63], v[62:63], v[150:151] op_sel_hi:[1,0]
	v_pk_mul_f32 v[64:65], v[64:65], v[150:151] op_sel_hi:[1,0]
	v_pk_mul_f32 v[130:131], v[130:131], v[150:151] op_sel_hi:[1,0]
	v_pk_mul_f32 v[132:133], v[132:133], v[150:151] op_sel_hi:[1,0]
	v_pk_mul_f32 v[62:63], v[192:193], v[62:63]
	v_pk_mul_f32 v[64:65], v[194:195], v[64:65]
	v_pk_mul_f32 v[130:131], v[196:197], v[130:131]
	v_pk_mul_f32 v[132:133], v[198:199], v[132:133]
	v_pk_mul_f32 v[58:59], v[54:55], v[130:131]
	v_pk_fma_f32 v[58:59], v[50:51], v[62:63], v[58:59] neg_lo:[0,0,1] neg_hi:[0,0,1]
	v_pk_mul_f32 v[60:61], v[56:57], v[132:133]
	v_pk_fma_f32 v[60:61], v[52:53], v[64:65], v[60:61] neg_lo:[0,0,1] neg_hi:[0,0,1]
	v_pk_mul_f32 v[130:131], v[50:51], v[130:131]
	v_pk_fma_f32 v[130:131], v[54:55], v[62:63], v[130:131]
	v_pk_mul_f32 v[132:133], v[52:53], v[132:133]
	v_pk_fma_f32 v[132:133], v[56:57], v[64:65], v[132:133]
	v_cvt_pk_bf16_f32 v62, v58, v59
	v_cvt_pk_bf16_f32 v63, v60, v61
	v_cvt_pk_bf16_f32 v64, v130, v131
	v_cvt_pk_bf16_f32 v65, v132, v133
	v_sub_u32_e32 v152, v208, v144
	global_store_dwordx2 v152, v[62:63], s[12:13] offset:128
	global_store_dwordx2 v152, v[64:65], s[12:13] offset:160
	v_mov_b32_e32 v208, v204
	global_load_dwordx2 v[42:43], v205, s[92:93] offset:768
	global_load_dwordx2 v[44:45], v205, s[92:93] offset:800
	global_load_dwordx4 v[34:37], v206, s[14:15]
	global_load_dwordx4 v[38:41], v206, s[14:15] offset:64
	v_add_u32_e32 v205, 0x4000, v205
	v_add_u32_e32 v206, 0x800, v206
	v_add_u32_e32 v204, 0xc00, v204
	v_fmamk_f32 v156, v166, 0x3c000000, v231
	v_rsq_f32_e32 v156, v156
	v_pk_mul_f32 v[154:155], v[26:27], v[26:27]
	v_pk_fma_f32 v[154:155], v[28:29], v[28:29], v[154:155]
	v_pk_fma_f32 v[154:155], v[30:31], v[30:31], v[154:155]
	v_pk_fma_f32 v[154:155], v[32:33], v[32:33], v[154:155]
	v_pk_fma_f32 v[154:155], v[22:23], v[22:23], v[154:155]
	v_pk_fma_f32 v[154:155], v[24:25], v[24:25], v[154:155]
	v_pk_fma_f32 v[154:155], v[18:19], v[18:19], v[154:155]
	v_pk_fma_f32 v[154:155], v[20:21], v[20:21], v[154:155]
	v_add_f32_e32 v154, v154, v155
	v_mov_b32_e32 v152, v154
	s_nop 1
	v_permlane16_swap_b32_e32 v154, v152
	v_add_f32_e32 v154, v154, v152
	v_mov_b32_e32 v152, v154
	s_nop 1
	v_permlane32_swap_b32_e32 v154, v152
	v_add_f32_e32 v154, v154, v152
	v_mul_f32_e32 v152, v156, v154
	v_fma_f32 v152, v156, v152, v174
	v_fmamk_f32 v152, v152, 0x3c2aaaab, v231
	v_rsq_f32_e32 v157, v152
	s_nop 0
	v_mul_f32_e32 v150, v156, v157
	v_pk_mul_f32 v[130:131], v[26:27], v[150:151] op_sel_hi:[1,0]
	v_pk_mul_f32 v[130:131], v[176:177], v[130:131]
	v_cvt_pk_bf16_f32 v200, v130, v131
	v_pk_mul_f32 v[132:133], v[28:29], v[150:151] op_sel_hi:[1,0]
	v_pk_mul_f32 v[132:133], v[178:179], v[132:133]
	v_cvt_pk_bf16_f32 v201, v132, v133
	v_pk_mul_f32 v[130:131], v[30:31], v[150:151] op_sel_hi:[1,0]
	v_pk_mul_f32 v[130:131], v[180:181], v[130:131]
	v_cvt_pk_bf16_f32 v202, v130, v131
	v_pk_mul_f32 v[132:133], v[32:33], v[150:151] op_sel_hi:[1,0]
	v_pk_mul_f32 v[132:133], v[182:183], v[132:133]
	v_cvt_pk_bf16_f32 v203, v132, v133
	global_store_dwordx4 v204, v[200:203], s[12:13]
	v_pk_mul_f32 v[130:131], v[22:23], v[150:151] op_sel_hi:[1,0]
	v_pk_mul_f32 v[130:131], v[184:185], v[130:131]
	v_cvt_pk_bf16_f32 v200, v130, v131
	v_pk_mul_f32 v[132:133], v[24:25], v[150:151] op_sel_hi:[1,0]
	v_pk_mul_f32 v[132:133], v[186:187], v[132:133]
	v_cvt_pk_bf16_f32 v201, v132, v133
	v_pk_mul_f32 v[130:131], v[18:19], v[150:151] op_sel_hi:[1,0]
	v_pk_mul_f32 v[130:131], v[188:189], v[130:131]
	v_cvt_pk_bf16_f32 v202, v130, v131
	v_pk_mul_f32 v[132:133], v[20:21], v[150:151] op_sel_hi:[1,0]
	v_pk_mul_f32 v[132:133], v[190:191], v[132:133]
	v_cvt_pk_bf16_f32 v203, v132, v133
	global_store_dwordx4 v204, v[200:203], s[12:13] offset:64
	s_waitcnt vmcnt(2)
	v_lshlrev_b32_e32 v46, 16, v42
	v_and_b32_e32 v47, 0xffff0000, v42
	v_lshlrev_b32_e32 v48, 16, v43
	v_and_b32_e32 v49, 0xffff0000, v43
	v_lshlrev_b32_e32 v130, 16, v44
	v_and_b32_e32 v131, 0xffff0000, v44
	v_lshlrev_b32_e32 v132, 16, v45
	v_and_b32_e32 v133, 0xffff0000, v45
	v_mov_b32_e32 v150, v158
	v_pk_mul_f32 v[46:47], v[46:47], v[150:151] op_sel_hi:[1,0]
	v_pk_mul_f32 v[48:49], v[48:49], v[150:151] op_sel_hi:[1,0]
	v_pk_mul_f32 v[130:131], v[130:131], v[150:151] op_sel_hi:[1,0]
	v_pk_mul_f32 v[132:133], v[132:133], v[150:151] op_sel_hi:[1,0]
	v_pk_mul_f32 v[46:47], v[192:193], v[46:47]
	v_pk_mul_f32 v[48:49], v[194:195], v[48:49]
	v_pk_mul_f32 v[130:131], v[196:197], v[130:131]
	v_pk_mul_f32 v[132:133], v[198:199], v[132:133]
	v_pk_mul_f32 v[42:43], v[38:39], v[130:131]
	v_pk_fma_f32 v[42:43], v[34:35], v[46:47], v[42:43] neg_lo:[0,0,1] neg_hi:[0,0,1]
	v_pk_mul_f32 v[44:45], v[40:41], v[132:133]
	v_pk_fma_f32 v[44:45], v[36:37], v[48:49], v[44:45] neg_lo:[0,0,1] neg_hi:[0,0,1]
	v_pk_mul_f32 v[130:131], v[34:35], v[130:131]
	v_pk_fma_f32 v[130:131], v[38:39], v[46:47], v[130:131]
	v_pk_mul_f32 v[132:133], v[36:37], v[132:133]
	v_pk_fma_f32 v[132:133], v[40:41], v[48:49], v[132:133]
	v_cvt_pk_bf16_f32 v46, v42, v43
	v_cvt_pk_bf16_f32 v47, v44, v45
	v_cvt_pk_bf16_f32 v48, v130, v131
	v_cvt_pk_bf16_f32 v49, v132, v133
	v_sub_u32_e32 v152, v208, v144
	global_store_dwordx2 v152, v[46:47], s[12:13] offset:128
	global_store_dwordx2 v152, v[48:49], s[12:13] offset:160
	v_mov_b32_e32 v208, v204
	global_load_dwordx2 v[26:27], v205, s[92:93] offset:768
;     __device__ __forceinline__ void operator()(const f32x4 (&acc)[2][2][4][2], const Unit& u, int wr, int wc, int fr, int fq) const {
;     ...
;                         float s = 0.f;
; #pragma unroll
;                         for (int bj = 0; bj < 2; ++bj) { const f32x4 a = acc[ai][bj][m][0], b = acc[ai][bj][m][1]; s += ((a[0] * a[0] + a[1] * a[1]) + (a[2] * a[2] + a[3] * a[3])) + ((b[0] * b[0] + b[1] * b[1]) + (b[2] * b[2] + b[3] * b[3])); }
;                         s += __shfl_xor(s, 16); s += __shfl_xor(s, 32);
;                         const float rh = __builtin_amdgcn_rsqf((s * r * r + ssq_kr[row]) * (1.0f / 96.0f) + RMS_EPS); const float rr = r * rh;
; #pragma unroll
;                         for (int bj = 0; bj < 2; ++bj) { const f32x4 a = acc[ai][bj][m][0] * rr * *(const f32x4*)(kg + 32 * bj + 8 * fq), b = acc[ai][bj][m][1] * rr * *(const f32x4*)(kg + 32 * bj + 8 * fq + 4);
;                             u32x4 w; w.x = cvt_pk_bf16(a[0], a[1]); w.y = cvt_pk_bf16(a[2], a[3]); w.z = cvt_pk_bf16(b[0], b[1]); w.w = cvt_pk_bf16(b[2], b[3]);
;                             *(u32x4*)(Kp + hrow * 96 + 32 * bj + 8 * fq) = w; }
;                         rh8[ai][m] = rh;
;                     }
;                     asm volatile("" ::: "memory"); }
;             if (wc < 2) {
; #pragma unroll
;                 for (int ai = 0; ai < 2; ++ai)
; #pragma unroll
;                     for (int m = 0; m < 4; ++m) { const size_t row = rowb + ai * HALF + m * 16; const size_t hrow = ((((row >> 12) * 8 + head) << 12) + (row & 4095)); const float rh = rh8[ai][m];
;                         const bf16_t* krp = PA + row * 512 + 384; const float* rp = ROPE + row * 32;
;                         { const int i0 = 4 * fq; const u32x2 xa = *(const u32x2*)(krp + i0), xb = *(const u32x2*)(krp + 16 + i0);
;                             const f32x4 cs = *(const f32x4*)(rp + i0), sn = *(const f32x4*)(rp + 16 + i0), ga = *(const f32x4*)(kg + 64 + i0), gb = *(const f32x4*)(kg + 80 + i0);
;                             const f32x4 a = (f32x4){bf_lo(xa.x), bf_hi(xa.x), bf_lo(xa.y), bf_hi(xa.y)} * rh * ga, bb = (f32x4){bf_lo(xb.x), bf_hi(xb.x), bf_lo(xb.y), bf_hi(xb.y)} * rh * gb;
;                             const f32x4 o1_ = a * cs - bb * sn, o2_ = bb * cs + a * sn;
	global_load_dwordx2 v[28:29], v205, s[92:93] offset:800
	global_load_dwordx4 v[18:21], v206, s[14:15]
	global_load_dwordx4 v[22:25], v206, s[14:15] offset:64
	v_add_u32_e32 v205, 0x4000, v205
	v_add_u32_e32 v206, 0x800, v206
	v_add_u32_e32 v204, 0xc00, v204
	v_fmamk_f32 v156, v167, 0x3c000000, v231
	v_rsq_f32_e32 v156, v156
	v_pk_mul_f32 v[154:155], v[10:11], v[10:11]
	v_pk_fma_f32 v[154:155], v[12:13], v[12:13], v[154:155]
	v_pk_fma_f32 v[154:155], v[14:15], v[14:15], v[154:155]
	v_pk_fma_f32 v[154:155], v[16:17], v[16:17], v[154:155]
	v_pk_fma_f32 v[154:155], v[6:7], v[6:7], v[154:155]
	v_pk_fma_f32 v[154:155], v[8:9], v[8:9], v[154:155]
	v_pk_fma_f32 v[154:155], v[2:3], v[2:3], v[154:155]
	v_pk_fma_f32 v[154:155], v[4:5], v[4:5], v[154:155]
	v_add_f32_e32 v154, v154, v155
	v_mov_b32_e32 v152, v154
	s_nop 1
	v_permlane16_swap_b32_e32 v154, v152
	v_add_f32_e32 v154, v154, v152
	v_mov_b32_e32 v152, v154
	s_nop 1
	v_permlane32_swap_b32_e32 v154, v152
	v_add_f32_e32 v154, v154, v152
	v_mul_f32_e32 v152, v156, v154
	v_fma_f32 v152, v156, v152, v175
	v_fmamk_f32 v152, v152, 0x3c2aaaab, v231
	v_rsq_f32_e32 v158, v152
	s_nop 0
	v_mul_f32_e32 v150, v156, v158
	v_pk_mul_f32 v[130:131], v[10:11], v[150:151] op_sel_hi:[1,0]
	v_pk_mul_f32 v[130:131], v[176:177], v[130:131]
	v_cvt_pk_bf16_f32 v200, v130, v131
	v_pk_mul_f32 v[132:133], v[12:13], v[150:151] op_sel_hi:[1,0]
	v_pk_mul_f32 v[132:133], v[178:179], v[132:133]
	v_cvt_pk_bf16_f32 v201, v132, v133
	v_pk_mul_f32 v[130:131], v[14:15], v[150:151] op_sel_hi:[1,0]
	v_pk_mul_f32 v[130:131], v[180:181], v[130:131]
	v_cvt_pk_bf16_f32 v202, v130, v131
	v_pk_mul_f32 v[132:133], v[16:17], v[150:151] op_sel_hi:[1,0]
	v_pk_mul_f32 v[132:133], v[182:183], v[132:133]
	v_cvt_pk_bf16_f32 v203, v132, v133
	global_store_dwordx4 v204, v[200:203], s[12:13]
	v_pk_mul_f32 v[130:131], v[6:7], v[150:151] op_sel_hi:[1,0]
	v_pk_mul_f32 v[130:131], v[184:185], v[130:131]
	v_cvt_pk_bf16_f32 v200, v130, v131
	v_pk_mul_f32 v[132:133], v[8:9], v[150:151] op_sel_hi:[1,0]
	v_pk_mul_f32 v[132:133], v[186:187], v[132:133]
	v_cvt_pk_bf16_f32 v201, v132, v133
	v_pk_mul_f32 v[130:131], v[2:3], v[150:151] op_sel_hi:[1,0]
	v_pk_mul_f32 v[130:131], v[188:189], v[130:131]
	v_cvt_pk_bf16_f32 v202, v130, v131
	v_pk_mul_f32 v[132:133], v[4:5], v[150:151] op_sel_hi:[1,0]
	v_pk_mul_f32 v[132:133], v[190:191], v[132:133]
	v_cvt_pk_bf16_f32 v203, v132, v133
	global_store_dwordx4 v204, v[200:203], s[12:13] offset:64
	s_waitcnt vmcnt(2)
	v_lshlrev_b32_e32 v30, 16, v26
	v_and_b32_e32 v31, 0xffff0000, v26
	v_lshlrev_b32_e32 v32, 16, v27
	v_and_b32_e32 v33, 0xffff0000, v27
	v_lshlrev_b32_e32 v130, 16, v28
	v_and_b32_e32 v131, 0xffff0000, v28
	v_lshlrev_b32_e32 v132, 16, v29
	v_and_b32_e32 v133, 0xffff0000, v29
	v_mov_b32_e32 v150, v157
	v_pk_mul_f32 v[30:31], v[30:31], v[150:151] op_sel_hi:[1,0]
	v_pk_mul_f32 v[32:33], v[32:33], v[150:151] op_sel_hi:[1,0]
	v_pk_mul_f32 v[130:131], v[130:131], v[150:151] op_sel_hi:[1,0]
	v_pk_mul_f32 v[132:133], v[132:133], v[150:151] op_sel_hi:[1,0]
	v_pk_mul_f32 v[30:31], v[192:193], v[30:31]
	v_pk_mul_f32 v[32:33], v[194:195], v[32:33]
	v_pk_mul_f32 v[130:131], v[196:197], v[130:131]
	v_pk_mul_f32 v[132:133], v[198:199], v[132:133]
	v_pk_mul_f32 v[26:27], v[22:23], v[130:131]
	v_pk_fma_f32 v[26:27], v[18:19], v[30:31], v[26:27] neg_lo:[0,0,1] neg_hi:[0,0,1]
	v_pk_mul_f32 v[28:29], v[24:25], v[132:133]
	v_pk_fma_f32 v[28:29], v[20:21], v[32:33], v[28:29] neg_lo:[0,0,1] neg_hi:[0,0,1]
	v_pk_mul_f32 v[130:131], v[18:19], v[130:131]
	v_pk_fma_f32 v[130:131], v[22:23], v[30:31], v[130:131]
	v_pk_mul_f32 v[132:133], v[20:21], v[132:133]
	v_pk_fma_f32 v[132:133], v[24:25], v[32:33], v[132:133]
	v_cvt_pk_bf16_f32 v30, v26, v27
	v_cvt_pk_bf16_f32 v31, v28, v29
	v_cvt_pk_bf16_f32 v32, v130, v131
	v_cvt_pk_bf16_f32 v33, v132, v133
	v_sub_u32_e32 v152, v208, v144
	global_store_dwordx2 v152, v[30:31], s[12:13] offset:128
	global_store_dwordx2 v152, v[32:33], s[12:13] offset:160
	v_mov_b32_e32 v208, v204
	global_load_dwordx2 v[10:11], v205, s[92:93] offset:768
	global_load_dwordx2 v[12:13], v205, s[92:93] offset:800
	global_load_dwordx4 v[2:5], v206, s[14:15]
	global_load_dwordx4 v[6:9], v206, s[14:15] offset:64
	s_waitcnt vmcnt(0)
	v_lshlrev_b32_e32 v14, 16, v10
	v_and_b32_e32 v15, 0xffff0000, v10
	v_lshlrev_b32_e32 v16, 16, v11
	v_and_b32_e32 v17, 0xffff0000, v11
	v_lshlrev_b32_e32 v130, 16, v12
	v_and_b32_e32 v131, 0xffff0000, v12
	v_lshlrev_b32_e32 v132, 16, v13
	v_and_b32_e32 v133, 0xffff0000, v13
	v_mov_b32_e32 v150, v158
	v_pk_mul_f32 v[14:15], v[14:15], v[150:151] op_sel_hi:[1,0]
	v_pk_mul_f32 v[16:17], v[16:17], v[150:151] op_sel_hi:[1,0]
	v_pk_mul_f32 v[130:131], v[130:131], v[150:151] op_sel_hi:[1,0]
	v_pk_mul_f32 v[132:133], v[132:133], v[150:151] op_sel_hi:[1,0]
	v_pk_mul_f32 v[14:15], v[192:193], v[14:15]
	v_pk_mul_f32 v[16:17], v[194:195], v[16:17]
	v_pk_mul_f32 v[130:131], v[196:197], v[130:131]
	v_pk_mul_f32 v[132:133], v[198:199], v[132:133]
	v_pk_mul_f32 v[10:11], v[6:7], v[130:131]
	v_pk_fma_f32 v[10:11], v[2:3], v[14:15], v[10:11] neg_lo:[0,0,1] neg_hi:[0,0,1]
	v_pk_mul_f32 v[12:13], v[8:9], v[132:133]
	v_pk_fma_f32 v[12:13], v[4:5], v[16:17], v[12:13] neg_lo:[0,0,1] neg_hi:[0,0,1]
	v_pk_mul_f32 v[130:131], v[2:3], v[130:131]
	v_pk_fma_f32 v[130:131], v[6:7], v[14:15], v[130:131]
	v_pk_mul_f32 v[132:133], v[4:5], v[132:133]
	v_pk_fma_f32 v[132:133], v[8:9], v[16:17], v[132:133]
	v_cvt_pk_bf16_f32 v14, v10, v11
	v_cvt_pk_bf16_f32 v15, v12, v13
	v_cvt_pk_bf16_f32 v16, v130, v131
	v_cvt_pk_bf16_f32 v17, v132, v133
	v_sub_u32_e32 v152, v208, v144
	global_store_dwordx2 v152, v[14:15], s[12:13] offset:128
	global_store_dwordx2 v152, v[16:17], s[12:13] offset:160
	s_branch .LBB0_524
; __device__ __forceinline__ unsigned cvt_pk_bf16(float lo, float hi) { unsigned r; asm volatile("v_cvt_pk_bf16_f32 %0, %1, %2" : "=v"(r) : "v"(lo), "v"(hi)); return r; }
;     __device__ __forceinline__ void operator()(const f32x4 (&acc)[2][2][4][2], const Unit& u, int wr, int wc, int fr, int fq) const {
;     ...
;                 for (int m = 0; m < 4; ++m) { const size_t row = rowb + ai * HALF + m * 16; const float r = __builtin_amdgcn_rsqf(ssq_kv[row] * (1.0f / 128.0f) + RMS_EPS);
;                     const size_t hrow = ((((row >> 12) * 8 + head) << 12) + (row & 4095));
;                     if (wc >= 2) {
; #pragma unroll
;                         for (int bj = 0; bj < 2; ++bj) { const f32x4 a = acc[ai][bj][m][0] * r, b = acc[ai][bj][m][1] * r;
;                             u32x4 w; w.x = cvt_pk_bf16(a[0], a[1]); w.y = cvt_pk_bf16(a[2], a[3]); w.z = cvt_pk_bf16(b[0], b[1]); w.w = cvt_pk_bf16(b[2], b[3]);
;                             *(u32x4*)(Vp + hrow * 64 + 32 * bj + 8 * fq) = w; }
.Lqkv_orig:
	v_lshlrev_b32_e32 v204, 7, v146
	v_add_u32_e32 v204, v204, v0
	global_load_dword v160, v[148:149], off offset:0
	global_load_dword v161, v[148:149], off offset:64
	global_load_dword v162, v[148:149], off offset:128
	global_load_dword v163, v[148:149], off offset:192
	global_load_dword v164, v[148:149], off offset:512
	global_load_dword v165, v[148:149], off offset:576
	global_load_dword v166, v[148:149], off offset:640
	global_load_dword v167, v[148:149], off offset:704
	s_waitcnt vmcnt(0)
	v_fmamk_f32 v150, v160, 0x3c000000, v231
	v_rsq_f32_e32 v150, v150
	s_nop 0
	v_pk_mul_f32 v[130:131], v[114:115], v[150:151] op_sel_hi:[1,0]
	v_pk_mul_f32 v[132:133], v[116:117], v[150:151] op_sel_hi:[1,0]
	v_cvt_pk_bf16_f32 v200, v130, v131
	v_cvt_pk_bf16_f32 v201, v132, v133
	v_pk_mul_f32 v[130:131], v[118:119], v[150:151] op_sel_hi:[1,0]
	v_pk_mul_f32 v[132:133], v[120:121], v[150:151] op_sel_hi:[1,0]
	v_cvt_pk_bf16_f32 v202, v130, v131
	v_cvt_pk_bf16_f32 v203, v132, v133
	global_store_dwordx4 v204, v[200:203], s[44:45]
	v_pk_mul_f32 v[130:131], v[122:123], v[150:151] op_sel_hi:[1,0]
	v_pk_mul_f32 v[132:133], v[124:125], v[150:151] op_sel_hi:[1,0]
	v_cvt_pk_bf16_f32 v200, v130, v131
	v_cvt_pk_bf16_f32 v201, v132, v133
	v_pk_mul_f32 v[130:131], v[126:127], v[150:151] op_sel_hi:[1,0]
	v_pk_mul_f32 v[132:133], v[128:129], v[150:151] op_sel_hi:[1,0]
	v_cvt_pk_bf16_f32 v202, v130, v131
	v_cvt_pk_bf16_f32 v203, v132, v133
	global_store_dwordx4 v204, v[200:203], s[44:45] offset:64
	v_add_u32_e32 v204, 0x800, v204
	v_fmamk_f32 v150, v161, 0x3c000000, v231
	v_rsq_f32_e32 v150, v150
	s_nop 0
	v_pk_mul_f32 v[130:131], v[98:99], v[150:151] op_sel_hi:[1,0]
	v_pk_mul_f32 v[132:133], v[100:101], v[150:151] op_sel_hi:[1,0]
	v_cvt_pk_bf16_f32 v200, v130, v131
	v_cvt_pk_bf16_f32 v201, v132, v133
	v_pk_mul_f32 v[130:131], v[102:103], v[150:151] op_sel_hi:[1,0]
	v_pk_mul_f32 v[132:133], v[104:105], v[150:151] op_sel_hi:[1,0]
	v_cvt_pk_bf16_f32 v202, v130, v131
	v_cvt_pk_bf16_f32 v203, v132, v133
	global_store_dwordx4 v204, v[200:203], s[44:45]
	v_pk_mul_f32 v[130:131], v[106:107], v[150:151] op_sel_hi:[1,0]
	v_pk_mul_f32 v[132:133], v[108:109], v[150:151] op_sel_hi:[1,0]
	v_cvt_pk_bf16_f32 v200, v130, v131
	v_cvt_pk_bf16_f32 v201, v132, v133
	v_pk_mul_f32 v[130:131], v[110:111], v[150:151] op_sel_hi:[1,0]
	v_pk_mul_f32 v[132:133], v[112:113], v[150:151] op_sel_hi:[1,0]
	v_cvt_pk_bf16_f32 v202, v130, v131
	v_cvt_pk_bf16_f32 v203, v132, v133
	global_store_dwordx4 v204, v[200:203], s[44:45] offset:64
	v_add_u32_e32 v204, 0x800, v204
	v_fmamk_f32 v150, v162, 0x3c000000, v231
	v_rsq_f32_e32 v150, v150
	s_nop 0
	v_pk_mul_f32 v[130:131], v[82:83], v[150:151] op_sel_hi:[1,0]
	v_pk_mul_f32 v[132:133], v[84:85], v[150:151] op_sel_hi:[1,0]
	v_cvt_pk_bf16_f32 v200, v130, v131
	v_cvt_pk_bf16_f32 v201, v132, v133
	v_pk_mul_f32 v[130:131], v[86:87], v[150:151] op_sel_hi:[1,0]
	v_pk_mul_f32 v[132:133], v[88:89], v[150:151] op_sel_hi:[1,0]
	v_cvt_pk_bf16_f32 v202, v130, v131
	v_cvt_pk_bf16_f32 v203, v132, v133
	global_store_dwordx4 v204, v[200:203], s[44:45]
	v_pk_mul_f32 v[130:131], v[90:91], v[150:151] op_sel_hi:[1,0]
	v_pk_mul_f32 v[132:133], v[92:93], v[150:151] op_sel_hi:[1,0]
	v_cvt_pk_bf16_f32 v200, v130, v131
	v_cvt_pk_bf16_f32 v201, v132, v133
	v_pk_mul_f32 v[130:131], v[94:95], v[150:151] op_sel_hi:[1,0]
	v_pk_mul_f32 v[132:133], v[96:97], v[150:151] op_sel_hi:[1,0]
	v_cvt_pk_bf16_f32 v202, v130, v131
	v_cvt_pk_bf16_f32 v203, v132, v133
	global_store_dwordx4 v204, v[200:203], s[44:45] offset:64
	v_add_u32_e32 v204, 0x800, v204
	v_fmamk_f32 v150, v163, 0x3c000000, v231
	v_rsq_f32_e32 v150, v150
	s_nop 0
	v_pk_mul_f32 v[130:131], v[74:75], v[150:151] op_sel_hi:[1,0]
	v_pk_mul_f32 v[132:133], v[76:77], v[150:151] op_sel_hi:[1,0]
	v_cvt_pk_bf16_f32 v200, v130, v131
	v_cvt_pk_bf16_f32 v201, v132, v133
	v_pk_mul_f32 v[130:131], v[78:79], v[150:151] op_sel_hi:[1,0]
	v_pk_mul_f32 v[132:133], v[80:81], v[150:151] op_sel_hi:[1,0]
	v_cvt_pk_bf16_f32 v202, v130, v131
	v_cvt_pk_bf16_f32 v203, v132, v133
	global_store_dwordx4 v204, v[200:203], s[44:45]
	v_pk_mul_f32 v[130:131], v[70:71], v[150:151] op_sel_hi:[1,0]
	v_pk_mul_f32 v[132:133], v[72:73], v[150:151] op_sel_hi:[1,0]
	v_cvt_pk_bf16_f32 v200, v130, v131
	v_cvt_pk_bf16_f32 v201, v132, v133
	v_pk_mul_f32 v[130:131], v[66:67], v[150:151] op_sel_hi:[1,0]
	v_pk_mul_f32 v[132:133], v[68:69], v[150:151] op_sel_hi:[1,0]
	v_cvt_pk_bf16_f32 v202, v130, v131
	v_cvt_pk_bf16_f32 v203, v132, v133
	global_store_dwordx4 v204, v[200:203], s[44:45] offset:64
	v_add_u32_e32 v204, 0x2800, v204
	v_fmamk_f32 v150, v164, 0x3c000000, v231
	v_rsq_f32_e32 v150, v150
	s_nop 0
	v_pk_mul_f32 v[130:131], v[58:59], v[150:151] op_sel_hi:[1,0]
	v_pk_mul_f32 v[132:133], v[60:61], v[150:151] op_sel_hi:[1,0]
	v_cvt_pk_bf16_f32 v200, v130, v131
	v_cvt_pk_bf16_f32 v201, v132, v133
	v_pk_mul_f32 v[130:131], v[62:63], v[150:151] op_sel_hi:[1,0]
	v_pk_mul_f32 v[132:133], v[64:65], v[150:151] op_sel_hi:[1,0]
	v_cvt_pk_bf16_f32 v202, v130, v131
	v_cvt_pk_bf16_f32 v203, v132, v133
	global_store_dwordx4 v204, v[200:203], s[44:45]
	v_pk_mul_f32 v[130:131], v[54:55], v[150:151] op_sel_hi:[1,0]
	v_pk_mul_f32 v[132:133], v[56:57], v[150:151] op_sel_hi:[1,0]
	v_cvt_pk_bf16_f32 v200, v130, v131
	v_cvt_pk_bf16_f32 v201, v132, v133
	v_pk_mul_f32 v[130:131], v[50:51], v[150:151] op_sel_hi:[1,0]
	v_pk_mul_f32 v[132:133], v[52:53], v[150:151] op_sel_hi:[1,0]
	v_cvt_pk_bf16_f32 v202, v130, v131
	v_cvt_pk_bf16_f32 v203, v132, v133
	global_store_dwordx4 v204, v[200:203], s[44:45] offset:64
	v_add_u32_e32 v204, 0x800, v204
	v_fmamk_f32 v150, v165, 0x3c000000, v231
; __device__ __forceinline__ unsigned cvt_pk_bf16(float lo, float hi) { unsigned r; asm volatile("v_cvt_pk_bf16_f32 %0, %1, %2" : "=v"(r) : "v"(lo), "v"(hi)); return r; }
;     __device__ __forceinline__ void operator()(const f32x4 (&acc)[2][2][4][2], const Unit& u, int wr, int wc, int fr, int fq) const {
;     ...
;                 for (int m = 0; m < 4; ++m) { const size_t row = rowb + ai * HALF + m * 16; const float r = __builtin_amdgcn_rsqf(ssq_kv[row] * (1.0f / 128.0f) + RMS_EPS);
;                     const size_t hrow = ((((row >> 12) * 8 + head) << 12) + (row & 4095));
;                     if (wc >= 2) {
; #pragma unroll
;                         for (int bj = 0; bj < 2; ++bj) { const f32x4 a = acc[ai][bj][m][0] * r, b = acc[ai][bj][m][1] * r;
;                             u32x4 w; w.x = cvt_pk_bf16(a[0], a[1]); w.y = cvt_pk_bf16(a[2], a[3]); w.z = cvt_pk_bf16(b[0], b[1]); w.w = cvt_pk_bf16(b[2], b[3]);
;                             *(u32x4*)(Vp + hrow * 64 + 32 * bj + 8 * fq) = w; }
;                     } else {
;                         float s = 0.f;
; #pragma unroll
;                         for (int bj = 0; bj < 2; ++bj) { const f32x4 a = acc[ai][bj][m][0], b = acc[ai][bj][m][1]; s += ((a[0] * a[0] + a[1] * a[1]) + (a[2] * a[2] + a[3] * a[3])) + ((b[0] * b[0] + b[1] * b[1]) + (b[2] * b[2] + b[3] * b[3])); }
;                         s += __shfl_xor(s, 16); s += __shfl_xor(s, 32);
;                         const float rh = __builtin_amdgcn_rsqf((s * r * r + ssq_kr[row]) * (1.0f / 96.0f) + RMS_EPS); const float rr = r * rh;
; #pragma unroll
;                         for (int bj = 0; bj < 2; ++bj) { const f32x4 a = acc[ai][bj][m][0] * rr * *(const f32x4*)(kg + 32 * bj + 8 * fq), b = acc[ai][bj][m][1] * rr * *(const f32x4*)(kg + 32 * bj + 8 * fq + 4);
;                             u32x4 w; w.x = cvt_pk_bf16(a[0], a[1]); w.y = cvt_pk_bf16(a[2], a[3]); w.z = cvt_pk_bf16(b[0], b[1]); w.w = cvt_pk_bf16(b[2], b[3]);
;                             *(u32x4*)(Kp + hrow * 96 + 32 * bj + 8 * fq) = w; }
	v_rsq_f32_e32 v150, v150
	s_nop 0
	v_pk_mul_f32 v[130:131], v[42:43], v[150:151] op_sel_hi:[1,0]
	v_pk_mul_f32 v[132:133], v[44:45], v[150:151] op_sel_hi:[1,0]
	v_cvt_pk_bf16_f32 v200, v130, v131
	v_cvt_pk_bf16_f32 v201, v132, v133
	v_pk_mul_f32 v[130:131], v[46:47], v[150:151] op_sel_hi:[1,0]
	v_pk_mul_f32 v[132:133], v[48:49], v[150:151] op_sel_hi:[1,0]
	v_cvt_pk_bf16_f32 v202, v130, v131
	v_cvt_pk_bf16_f32 v203, v132, v133
	global_store_dwordx4 v204, v[200:203], s[44:45]
	v_pk_mul_f32 v[130:131], v[38:39], v[150:151] op_sel_hi:[1,0]
	v_pk_mul_f32 v[132:133], v[40:41], v[150:151] op_sel_hi:[1,0]
	v_cvt_pk_bf16_f32 v200, v130, v131
	v_cvt_pk_bf16_f32 v201, v132, v133
	v_pk_mul_f32 v[130:131], v[34:35], v[150:151] op_sel_hi:[1,0]
	v_pk_mul_f32 v[132:133], v[36:37], v[150:151] op_sel_hi:[1,0]
	v_cvt_pk_bf16_f32 v202, v130, v131
	v_cvt_pk_bf16_f32 v203, v132, v133
	global_store_dwordx4 v204, v[200:203], s[44:45] offset:64
	v_add_u32_e32 v204, 0x800, v204
	v_fmamk_f32 v150, v166, 0x3c000000, v231
	v_rsq_f32_e32 v150, v150
	s_nop 0
	v_pk_mul_f32 v[130:131], v[26:27], v[150:151] op_sel_hi:[1,0]
	v_pk_mul_f32 v[132:133], v[28:29], v[150:151] op_sel_hi:[1,0]
	v_cvt_pk_bf16_f32 v200, v130, v131
	v_cvt_pk_bf16_f32 v201, v132, v133
	v_pk_mul_f32 v[130:131], v[30:31], v[150:151] op_sel_hi:[1,0]
	v_pk_mul_f32 v[132:133], v[32:33], v[150:151] op_sel_hi:[1,0]
	v_cvt_pk_bf16_f32 v202, v130, v131
	v_cvt_pk_bf16_f32 v203, v132, v133
	global_store_dwordx4 v204, v[200:203], s[44:45]
	v_pk_mul_f32 v[130:131], v[22:23], v[150:151] op_sel_hi:[1,0]
	v_pk_mul_f32 v[132:133], v[24:25], v[150:151] op_sel_hi:[1,0]
	v_cvt_pk_bf16_f32 v200, v130, v131
	v_cvt_pk_bf16_f32 v201, v132, v133
	v_pk_mul_f32 v[130:131], v[18:19], v[150:151] op_sel_hi:[1,0]
	v_pk_mul_f32 v[132:133], v[20:21], v[150:151] op_sel_hi:[1,0]
	v_cvt_pk_bf16_f32 v202, v130, v131
	v_cvt_pk_bf16_f32 v203, v132, v133
	global_store_dwordx4 v204, v[200:203], s[44:45] offset:64
	v_add_u32_e32 v204, 0x800, v204
	v_fmamk_f32 v150, v167, 0x3c000000, v231
	v_rsq_f32_e32 v150, v150
	s_nop 0
	v_pk_mul_f32 v[130:131], v[10:11], v[150:151] op_sel_hi:[1,0]
	v_pk_mul_f32 v[132:133], v[12:13], v[150:151] op_sel_hi:[1,0]
	v_cvt_pk_bf16_f32 v200, v130, v131
	v_cvt_pk_bf16_f32 v201, v132, v133
	v_pk_mul_f32 v[130:131], v[14:15], v[150:151] op_sel_hi:[1,0]
	v_pk_mul_f32 v[132:133], v[16:17], v[150:151] op_sel_hi:[1,0]
	v_cvt_pk_bf16_f32 v202, v130, v131
	v_cvt_pk_bf16_f32 v203, v132, v133
	global_store_dwordx4 v204, v[200:203], s[44:45]
	v_pk_mul_f32 v[130:131], v[6:7], v[150:151] op_sel_hi:[1,0]
	v_pk_mul_f32 v[132:133], v[8:9], v[150:151] op_sel_hi:[1,0]
	v_cvt_pk_bf16_f32 v200, v130, v131
	v_cvt_pk_bf16_f32 v201, v132, v133
	v_pk_mul_f32 v[130:131], v[2:3], v[150:151] op_sel_hi:[1,0]
	v_pk_mul_f32 v[132:133], v[4:5], v[150:151] op_sel_hi:[1,0]
	v_cvt_pk_bf16_f32 v202, v130, v131
	v_cvt_pk_bf16_f32 v203, v132, v133
	global_store_dwordx4 v204, v[200:203], s[44:45] offset:64
	s_branch .LBB0_524
	s_waitcnt vmcnt(0) lgkmcnt(0)
	v_fmamk_f32 v130, v130, 0x3c000000, v231
	v_rsq_f32_e32 v150, v130
	s_cbranch_vccz .LBB0_491
	v_mov_b32_e32 v132, v115
	v_mov_b32_e32 v133, v123
	v_mov_b32_e32 v130, v114
	v_mov_b32_e32 v131, v122
	v_pk_mul_f32 v[132:133], v[132:133], v[132:133]
	v_mov_b32_e32 v154, v117
	v_mov_b32_e32 v155, v125
	v_pk_fma_f32 v[130:131], v[130:131], v[130:131], v[132:133]
	v_mov_b32_e32 v132, v116
	v_mov_b32_e32 v133, v124
	v_pk_mul_f32 v[154:155], v[154:155], v[154:155]
	v_mov_b32_e32 v160, v121
	v_pk_fma_f32 v[132:133], v[132:133], v[132:133], v[154:155]
	v_mov_b32_e32 v154, v119
	v_mov_b32_e32 v155, v127
	v_pk_add_f32 v[130:131], v[130:131], v[132:133]
	v_mov_b32_e32 v132, v118
	v_mov_b32_e32 v133, v126
	v_pk_mul_f32 v[154:155], v[154:155], v[154:155]
	v_mov_b32_e32 v161, v129
	v_pk_fma_f32 v[132:133], v[132:133], v[132:133], v[154:155]
	v_mov_b32_e32 v154, v120
	v_mov_b32_e32 v155, v128
	v_pk_mul_f32 v[160:161], v[160:161], v[160:161]
	s_nop 0
	v_pk_fma_f32 v[154:155], v[154:155], v[154:155], v[160:161]
	s_nop 0
	v_pk_add_f32 v[132:133], v[132:133], v[154:155]
	v_mad_u64_u32 v[154:155], s[34:35], v146, s33, v[156:157]
	v_pk_add_f32 v[130:131], v[130:131], v[132:133]
	v_and_b32_e32 v132, 64, v228
	v_add_f32_e32 v130, v130, v131
	v_xor_b32_e32 v131, 16, v228
	v_add_u32_e32 v132, 64, v132
	v_cmp_lt_i32_e32 vcc, v131, v132
	s_nop 1
	v_cndmask_b32_e32 v131, v228, v131, vcc
	v_lshlrev_b32_e32 v131, 2, v131
	ds_bpermute_b32 v131, v131, v130
	s_waitcnt lgkmcnt(0)
	v_add_f32_e32 v130, v130, v131
	v_xor_b32_e32 v131, 32, v228
	v_cmp_lt_i32_e32 vcc, v131, v132
	s_nop 1
	v_cndmask_b32_e32 v131, v228, v131, vcc
	v_lshlrev_b32_e32 v131, 2, v131
	ds_bpermute_b32 v131, v131, v130
	s_waitcnt lgkmcnt(0)
	v_add_f32_e32 v130, v130, v131
	v_mul_f32_e32 v132, v150, v130
	v_lshl_add_u64 v[130:131], v[142:143], 2, s[18:19]
	flat_load_dword v130, v[130:131]
	s_waitcnt vmcnt(0) lgkmcnt(0)
	v_fmac_f32_e32 v130, v150, v132
	v_fmamk_f32 v130, v130, 0x3c2aaaab, v231
	v_rsq_f32_e32 v152, v130
	v_mov_b32_e32 v130, v155
	v_mad_u64_u32 v[130:131], s[34:35], v147, s33, v[130:131]
	v_mov_b32_e32 v155, v130
	global_load_dwordx4 v[130:133], v145, s[8:9] offset:16
	global_load_dwordx4 v[160:163], v145, s[8:9]
	v_mul_f32_e32 v158, v150, v152
	v_pk_mul_f32 v[164:165], v[114:115], v[158:159] op_sel_hi:[1,0]
	v_pk_mul_f32 v[168:169], v[116:117], v[158:159] op_sel_hi:[1,0]
	s_mov_b64 s[34:35], 0
	s_waitcnt vmcnt(0)
	v_pk_mul_f32 v[162:163], v[162:163], v[168:169]
	v_pk_mul_f32 v[160:161], v[160:161], v[164:165]
	v_pk_mul_f32 v[164:165], v[118:119], v[158:159] op_sel_hi:[1,0]
	v_pk_mul_f32 v[168:169], v[120:121], v[158:159] op_sel_hi:[1,0]
	s_nop 0
	v_pk_mul_f32 v[168:169], v[132:133], v[168:169]
	v_pk_mul_f32 v[132:133], v[130:131], v[164:165]
	v_cvt_pk_bf16_f32 v130, v160, v161
	v_cvt_pk_bf16_f32 v131, v162, v163
	v_pk_mul_f32 v[164:165], v[122:123], v[158:159] op_sel_hi:[1,0]
	v_cvt_pk_bf16_f32 v132, v132, v133
	v_cvt_pk_bf16_f32 v133, v168, v169
	flat_store_dwordx4 v[154:155], v[130:133]
	global_load_dwordx4 v[130:133], v145, s[8:9] offset:144
	s_nop 0
	global_load_dwordx4 v[160:163], v145, s[8:9] offset:128
	v_pk_mul_f32 v[168:169], v[124:125], v[158:159] op_sel_hi:[1,0]
	s_waitcnt vmcnt(0)
	v_pk_mul_f32 v[160:161], v[160:161], v[164:165]
	v_pk_mul_f32 v[162:163], v[162:163], v[168:169]
	v_pk_mul_f32 v[164:165], v[126:127], v[158:159] op_sel_hi:[1,0]
	v_pk_mul_f32 v[168:169], v[128:129], v[158:159] op_sel_hi:[1,0]
	s_nop 0
	v_pk_mul_f32 v[168:169], v[132:133], v[168:169]
	v_pk_mul_f32 v[132:133], v[130:131], v[164:165]
	v_cvt_pk_bf16_f32 v130, v160, v161
	v_cvt_pk_bf16_f32 v131, v162, v163
	s_nop 0
	v_cvt_pk_bf16_f32 v132, v132, v133
	v_cvt_pk_bf16_f32 v133, v168, v169

; __device__ __forceinline__ unsigned cvt_pk_bf16(float lo, float hi) { unsigned r; asm volatile("v_cvt_pk_bf16_f32 %0, %1, %2" : "=v"(r) : "v"(lo), "v"(hi)); return r; }
;     __device__ __forceinline__ void operator()(const f32x4 (&acc)[2][2][4][2], const Unit& u, int wr, int wc, int fr, int fq) const {
;     ...
;         if (u.pn < 3) {
;             const int col0 = u.pn * BM + wc * 32 + 8 * fq;
; #pragma unroll
;             for (int ai = 0; ai < 2; ++ai)
; #pragma unroll
;                 for (int m = 0; m < 4; ++m) { const size_t row = rowb + ai * HALF + m * 16; const float r = __builtin_amdgcn_rsqf(ssq_q[row] * (1.0f / 256.0f) + RMS_EPS);
; #pragma unroll
;                     for (int bj = 0; bj < 2; ++bj) { const f32x4 v0 = acc[ai][bj][m][0] * r, v1 = acc[ai][bj][m][1] * r;
;                         u32x4 w; w.x = cvt_pk_bf16(v0[0], v0[1]); w.y = cvt_pk_bf16(v0[2], v0[3]); w.z = cvt_pk_bf16(v1[0], v1[1]); w.w = cvt_pk_bf16(v1[2], v1[3]);
;                         *(u32x4*)(Oq + row * 768 + col0 + bj * HALF) = w; } }
.LBB0_525:
	s_and_b64 vcc, exec, s[34:35]
	s_cbranch_vccz .LBB0_524
	s_lshl_b32 s2, s60, 8
	s_or_b32 s2, s2, s73
	v_lshl_or_b32 v130, v167, 3, s2
	v_mul_u32_u24_e32 v204, 0x600, v142
	v_lshl_add_u32 v204, v130, 1, v204
	v_lshlrev_b32_e32 v146, 2, v142
	global_load_dword v160, v146, s[48:49] offset:0
	global_load_dword v161, v146, s[48:49] offset:64
	global_load_dword v162, v146, s[48:49] offset:128
	global_load_dword v163, v146, s[48:49] offset:192
	global_load_dword v164, v146, s[48:49] offset:512
	global_load_dword v165, v146, s[48:49] offset:576
	global_load_dword v166, v146, s[48:49] offset:640
	global_load_dword v167, v146, s[48:49] offset:704
	s_waitcnt vmcnt(0)
	v_fmamk_f32 v150, v160, 0x3b800000, v231
	v_rsq_f32_e32 v150, v150
	s_nop 0
	v_pk_mul_f32 v[130:131], v[114:115], v[150:151] op_sel_hi:[1,0]
	v_pk_mul_f32 v[132:133], v[116:117], v[150:151] op_sel_hi:[1,0]
	v_cvt_pk_bf16_f32 v200, v130, v131
	v_cvt_pk_bf16_f32 v201, v132, v133
	v_pk_mul_f32 v[130:131], v[118:119], v[150:151] op_sel_hi:[1,0]
	v_pk_mul_f32 v[132:133], v[120:121], v[150:151] op_sel_hi:[1,0]
	v_cvt_pk_bf16_f32 v202, v130, v131
	v_cvt_pk_bf16_f32 v203, v132, v133
	global_store_dwordx4 v204, v[200:203], s[92:93]
	v_pk_mul_f32 v[130:131], v[122:123], v[150:151] op_sel_hi:[1,0]
	v_pk_mul_f32 v[132:133], v[124:125], v[150:151] op_sel_hi:[1,0]
	v_cvt_pk_bf16_f32 v200, v130, v131
	v_cvt_pk_bf16_f32 v201, v132, v133
	v_pk_mul_f32 v[130:131], v[126:127], v[150:151] op_sel_hi:[1,0]
	v_pk_mul_f32 v[132:133], v[128:129], v[150:151] op_sel_hi:[1,0]
	v_cvt_pk_bf16_f32 v202, v130, v131
	v_cvt_pk_bf16_f32 v203, v132, v133
	global_store_dwordx4 v204, v[200:203], s[92:93] offset:256
	v_add_u32_e32 v204, 0x6000, v204
	v_fmamk_f32 v150, v161, 0x3b800000, v231
	v_rsq_f32_e32 v150, v150
	s_nop 0
	v_pk_mul_f32 v[130:131], v[98:99], v[150:151] op_sel_hi:[1,0]
	v_pk_mul_f32 v[132:133], v[100:101], v[150:151] op_sel_hi:[1,0]
	v_cvt_pk_bf16_f32 v200, v130, v131
	v_cvt_pk_bf16_f32 v201, v132, v133
	v_pk_mul_f32 v[130:131], v[102:103], v[150:151] op_sel_hi:[1,0]
	v_pk_mul_f32 v[132:133], v[104:105], v[150:151] op_sel_hi:[1,0]
	v_cvt_pk_bf16_f32 v202, v130, v131
	v_cvt_pk_bf16_f32 v203, v132, v133
	global_store_dwordx4 v204, v[200:203], s[92:93]
	v_pk_mul_f32 v[130:131], v[106:107], v[150:151] op_sel_hi:[1,0]
	v_pk_mul_f32 v[132:133], v[108:109], v[150:151] op_sel_hi:[1,0]
	v_cvt_pk_bf16_f32 v200, v130, v131
	v_cvt_pk_bf16_f32 v201, v132, v133
	v_pk_mul_f32 v[130:131], v[110:111], v[150:151] op_sel_hi:[1,0]
	v_pk_mul_f32 v[132:133], v[112:113], v[150:151] op_sel_hi:[1,0]
	v_cvt_pk_bf16_f32 v202, v130, v131
	v_cvt_pk_bf16_f32 v203, v132, v133
	global_store_dwordx4 v204, v[200:203], s[92:93] offset:256
	v_add_u32_e32 v204, 0x6000, v204
	v_fmamk_f32 v150, v162, 0x3b800000, v231
	v_rsq_f32_e32 v150, v150
	s_nop 0
	v_pk_mul_f32 v[130:131], v[82:83], v[150:151] op_sel_hi:[1,0]
	v_pk_mul_f32 v[132:133], v[84:85], v[150:151] op_sel_hi:[1,0]
	v_cvt_pk_bf16_f32 v200, v130, v131
	v_cvt_pk_bf16_f32 v201, v132, v133
	v_pk_mul_f32 v[130:131], v[86:87], v[150:151] op_sel_hi:[1,0]
	v_pk_mul_f32 v[132:133], v[88:89], v[150:151] op_sel_hi:[1,0]
	v_cvt_pk_bf16_f32 v202, v130, v131
	v_cvt_pk_bf16_f32 v203, v132, v133
	global_store_dwordx4 v204, v[200:203], s[92:93]
	v_pk_mul_f32 v[130:131], v[90:91], v[150:151] op_sel_hi:[1,0]
	v_pk_mul_f32 v[132:133], v[92:93], v[150:151] op_sel_hi:[1,0]
	v_cvt_pk_bf16_f32 v200, v130, v131
	v_cvt_pk_bf16_f32 v201, v132, v133
	v_pk_mul_f32 v[130:131], v[94:95], v[150:151] op_sel_hi:[1,0]
	v_pk_mul_f32 v[132:133], v[96:97], v[150:151] op_sel_hi:[1,0]
	v_cvt_pk_bf16_f32 v202, v130, v131
	v_cvt_pk_bf16_f32 v203, v132, v133
	global_store_dwordx4 v204, v[200:203], s[92:93] offset:256
	v_add_u32_e32 v204, 0x6000, v204
	v_fmamk_f32 v150, v163, 0x3b800000, v231
	v_rsq_f32_e32 v150, v150
	s_nop 0
	v_pk_mul_f32 v[130:131], v[74:75], v[150:151] op_sel_hi:[1,0]
	v_pk_mul_f32 v[132:133], v[76:77], v[150:151] op_sel_hi:[1,0]
	v_cvt_pk_bf16_f32 v200, v130, v131
	v_cvt_pk_bf16_f32 v201, v132, v133
	v_pk_mul_f32 v[130:131], v[78:79], v[150:151] op_sel_hi:[1,0]
	v_pk_mul_f32 v[132:133], v[80:81], v[150:151] op_sel_hi:[1,0]
	v_cvt_pk_bf16_f32 v202, v130, v131
	v_cvt_pk_bf16_f32 v203, v132, v133
	global_store_dwordx4 v204, v[200:203], s[92:93]
	v_pk_mul_f32 v[130:131], v[70:71], v[150:151] op_sel_hi:[1,0]
	v_pk_mul_f32 v[132:133], v[72:73], v[150:151] op_sel_hi:[1,0]
	v_cvt_pk_bf16_f32 v200, v130, v131
	v_cvt_pk_bf16_f32 v201, v132, v133
	v_pk_mul_f32 v[130:131], v[66:67], v[150:151] op_sel_hi:[1,0]
	v_pk_mul_f32 v[132:133], v[68:69], v[150:151] op_sel_hi:[1,0]
	v_cvt_pk_bf16_f32 v202, v130, v131
	v_cvt_pk_bf16_f32 v203, v132, v133
	global_store_dwordx4 v204, v[200:203], s[92:93] offset:256
	v_add_u32_e32 v204, 0x1e000, v204
	v_fmamk_f32 v150, v164, 0x3b800000, v231
	v_rsq_f32_e32 v150, v150
	s_nop 0
	v_pk_mul_f32 v[130:131], v[58:59], v[150:151] op_sel_hi:[1,0]
	v_pk_mul_f32 v[132:133], v[60:61], v[150:151] op_sel_hi:[1,0]
	v_cvt_pk_bf16_f32 v200, v130, v131
	v_cvt_pk_bf16_f32 v201, v132, v133
	v_pk_mul_f32 v[130:131], v[62:63], v[150:151] op_sel_hi:[1,0]
	v_pk_mul_f32 v[132:133], v[64:65], v[150:151] op_sel_hi:[1,0]
	v_cvt_pk_bf16_f32 v202, v130, v131
	v_cvt_pk_bf16_f32 v203, v132, v133
	global_store_dwordx4 v204, v[200:203], s[92:93]
	v_pk_mul_f32 v[130:131], v[54:55], v[150:151] op_sel_hi:[1,0]
	v_pk_mul_f32 v[132:133], v[56:57], v[150:151] op_sel_hi:[1,0]
	v_cvt_pk_bf16_f32 v200, v130, v131
	v_cvt_pk_bf16_f32 v201, v132, v133
	v_pk_mul_f32 v[130:131], v[50:51], v[150:151] op_sel_hi:[1,0]
	v_pk_mul_f32 v[132:133], v[52:53], v[150:151] op_sel_hi:[1,0]
	v_cvt_pk_bf16_f32 v202, v130, v131
; __device__ __forceinline__ unsigned cvt_pk_bf16(float lo, float hi) { unsigned r; asm volatile("v_cvt_pk_bf16_f32 %0, %1, %2" : "=v"(r) : "v"(lo), "v"(hi)); return r; }
;     __device__ __forceinline__ void operator()(const f32x4 (&acc)[2][2][4][2], const Unit& u, int wr, int wc, int fr, int fq) const {
;     ...
;         if (u.pn < 3) {
;             const int col0 = u.pn * BM + wc * 32 + 8 * fq;
; #pragma unroll
;             for (int ai = 0; ai < 2; ++ai)
; #pragma unroll
;                 for (int m = 0; m < 4; ++m) { const size_t row = rowb + ai * HALF + m * 16; const float r = __builtin_amdgcn_rsqf(ssq_q[row] * (1.0f / 256.0f) + RMS_EPS);
; #pragma unroll
;                     for (int bj = 0; bj < 2; ++bj) { const f32x4 v0 = acc[ai][bj][m][0] * r, v1 = acc[ai][bj][m][1] * r;
;                         u32x4 w; w.x = cvt_pk_bf16(v0[0], v0[1]); w.y = cvt_pk_bf16(v0[2], v0[3]); w.z = cvt_pk_bf16(v1[0], v1[1]); w.w = cvt_pk_bf16(v1[2], v1[3]);
;                         *(u32x4*)(Oq + row * 768 + col0 + bj * HALF) = w; } }
	v_cvt_pk_bf16_f32 v203, v132, v133
	global_store_dwordx4 v204, v[200:203], s[92:93] offset:256
	v_add_u32_e32 v204, 0x6000, v204
	v_fmamk_f32 v150, v165, 0x3b800000, v231
	v_rsq_f32_e32 v150, v150
	s_nop 0
	v_pk_mul_f32 v[130:131], v[42:43], v[150:151] op_sel_hi:[1,0]
	v_pk_mul_f32 v[132:133], v[44:45], v[150:151] op_sel_hi:[1,0]
	v_cvt_pk_bf16_f32 v200, v130, v131
	v_cvt_pk_bf16_f32 v201, v132, v133
	v_pk_mul_f32 v[130:131], v[46:47], v[150:151] op_sel_hi:[1,0]
	v_pk_mul_f32 v[132:133], v[48:49], v[150:151] op_sel_hi:[1,0]
	v_cvt_pk_bf16_f32 v202, v130, v131
	v_cvt_pk_bf16_f32 v203, v132, v133
	global_store_dwordx4 v204, v[200:203], s[92:93]
	v_pk_mul_f32 v[130:131], v[38:39], v[150:151] op_sel_hi:[1,0]
	v_pk_mul_f32 v[132:133], v[40:41], v[150:151] op_sel_hi:[1,0]
	v_cvt_pk_bf16_f32 v200, v130, v131
	v_cvt_pk_bf16_f32 v201, v132, v133
	v_pk_mul_f32 v[130:131], v[34:35], v[150:151] op_sel_hi:[1,0]
	v_pk_mul_f32 v[132:133], v[36:37], v[150:151] op_sel_hi:[1,0]
	v_cvt_pk_bf16_f32 v202, v130, v131
	v_cvt_pk_bf16_f32 v203, v132, v133
	global_store_dwordx4 v204, v[200:203], s[92:93] offset:256
	v_add_u32_e32 v204, 0x6000, v204
	v_fmamk_f32 v150, v166, 0x3b800000, v231
	v_rsq_f32_e32 v150, v150
	s_nop 0
	v_pk_mul_f32 v[130:131], v[26:27], v[150:151] op_sel_hi:[1,0]
	v_pk_mul_f32 v[132:133], v[28:29], v[150:151] op_sel_hi:[1,0]
	v_cvt_pk_bf16_f32 v200, v130, v131
	v_cvt_pk_bf16_f32 v201, v132, v133
	v_pk_mul_f32 v[130:131], v[30:31], v[150:151] op_sel_hi:[1,0]
	v_pk_mul_f32 v[132:133], v[32:33], v[150:151] op_sel_hi:[1,0]
	v_cvt_pk_bf16_f32 v202, v130, v131
	v_cvt_pk_bf16_f32 v203, v132, v133
	global_store_dwordx4 v204, v[200:203], s[92:93]
	v_pk_mul_f32 v[130:131], v[22:23], v[150:151] op_sel_hi:[1,0]
	v_pk_mul_f32 v[132:133], v[24:25], v[150:151] op_sel_hi:[1,0]
	v_cvt_pk_bf16_f32 v200, v130, v131
	v_cvt_pk_bf16_f32 v201, v132, v133
	v_pk_mul_f32 v[130:131], v[18:19], v[150:151] op_sel_hi:[1,0]
	v_pk_mul_f32 v[132:133], v[20:21], v[150:151] op_sel_hi:[1,0]
	v_cvt_pk_bf16_f32 v202, v130, v131
	v_cvt_pk_bf16_f32 v203, v132, v133
	global_store_dwordx4 v204, v[200:203], s[92:93] offset:256
	v_add_u32_e32 v204, 0x6000, v204
	v_fmamk_f32 v150, v167, 0x3b800000, v231
	v_rsq_f32_e32 v150, v150
	s_nop 0
	v_pk_mul_f32 v[130:131], v[10:11], v[150:151] op_sel_hi:[1,0]
	v_pk_mul_f32 v[132:133], v[12:13], v[150:151] op_sel_hi:[1,0]
	v_cvt_pk_bf16_f32 v200, v130, v131
	v_cvt_pk_bf16_f32 v201, v132, v133
	v_pk_mul_f32 v[130:131], v[14:15], v[150:151] op_sel_hi:[1,0]
	v_pk_mul_f32 v[132:133], v[16:17], v[150:151] op_sel_hi:[1,0]
	v_cvt_pk_bf16_f32 v202, v130, v131
	v_cvt_pk_bf16_f32 v203, v132, v133
	global_store_dwordx4 v204, v[200:203], s[92:93]
	v_pk_mul_f32 v[130:131], v[6:7], v[150:151] op_sel_hi:[1,0]
	v_pk_mul_f32 v[132:133], v[8:9], v[150:151] op_sel_hi:[1,0]
	v_cvt_pk_bf16_f32 v200, v130, v131
	v_cvt_pk_bf16_f32 v201, v132, v133
	v_pk_mul_f32 v[130:131], v[2:3], v[150:151] op_sel_hi:[1,0]
	v_pk_mul_f32 v[132:133], v[4:5], v[150:151] op_sel_hi:[1,0]
	v_cvt_pk_bf16_f32 v202, v130, v131
	v_cvt_pk_bf16_f32 v203, v132, v133
	global_store_dwordx4 v204, v[200:203], s[92:93] offset:256
	s_branch .LBB0_524
	v_lshlrev_b64 v[146:147], 2, v[142:143]
	v_lshl_add_u64 v[144:145], s[48:49], 0, v[146:147]
	flat_load_dword v0, v[144:145]
	s_lshl_b32 s2, s60, 8
	s_or_b32 s2, s2, s73
	v_lshl_or_b32 v130, v167, 3, s2
	v_ashrrev_i32_e32 v131, 31, v130
	v_lshl_add_u64 v[130:131], v[130:131], 1, s[92:93]
	s_movk_i32 s30, 0x600
	v_mad_u64_u32 v[132:133], s[2:3], v142, s30, v[130:131]
	v_mov_b32_e32 v130, v133
	v_mad_u64_u32 v[130:131], s[2:3], v143, s30, v[130:131]
	v_mov_b32_e32 v133, v130
	s_mov_b64 s[2:3], 0xc000
	s_waitcnt vmcnt(0) lgkmcnt(0)
	v_fmamk_f32 v0, v0, 0x3b800000, v231
	v_rsq_f32_e32 v0, v0
	s_nop 0
	v_pk_mul_f32 v[114:115], v[114:115], v[0:1] op_sel_hi:[1,0]
	v_pk_mul_f32 v[116:117], v[116:117], v[0:1] op_sel_hi:[1,0]
	v_cvt_pk_bf16_f32 v114, v114, v115
	v_pk_mul_f32 v[120:121], v[120:121], v[0:1] op_sel_hi:[1,0]
	v_cvt_pk_bf16_f32 v115, v116, v117
	v_pk_mul_f32 v[118:119], v[118:119], v[0:1] op_sel_hi:[1,0]
	s_nop 0
	v_cvt_pk_bf16_f32 v116, v118, v119
	v_cvt_pk_bf16_f32 v117, v120, v121
	flat_store_dwordx4 v[132:133], v[114:117]
	v_pk_mul_f32 v[118:119], v[128:129], v[0:1] op_sel_hi:[1,0]
	v_pk_mul_f32 v[120:121], v[126:127], v[0:1] op_sel_hi:[1,0]
	v_pk_mul_f32 v[114:115], v[122:123], v[0:1] op_sel_hi:[1,0]
	v_pk_mul_f32 v[116:117], v[124:125], v[0:1] op_sel_hi:[1,0]
	v_cvt_pk_bf16_f32 v114, v114, v115
	s_nop 0
	v_cvt_pk_bf16_f32 v115, v116, v117
	v_cvt_pk_bf16_f32 v116, v120, v121
	v_cvt_pk_bf16_f32 v117, v118, v119
	flat_store_dwordx4 v[132:133], v[114:117] offset:256
	s_nop 1
	v_or_b32_e32 v114, 64, v146
	v_mov_b32_e32 v115, v147
	v_lshl_add_u64 v[114:115], s[48:49], 0, v[114:115]
	flat_load_dword v0, v[114:115]
	v_lshl_add_u64 v[114:115], v[132:133], 0, s[0:1]
	s_waitcnt vmcnt(0) lgkmcnt(0)
	v_fmamk_f32 v0, v0, 0x3b800000, v231
	v_rsq_f32_e32 v0, v0
	s_nop 0
	v_pk_mul_f32 v[100:101], v[100:101], v[0:1] op_sel_hi:[1,0]
	v_pk_mul_f32 v[98:99], v[98:99], v[0:1] op_sel_hi:[1,0]
	v_pk_mul_f32 v[102:103], v[102:103], v[0:1] op_sel_hi:[1,0]
	v_cvt_pk_bf16_f32 v98, v98, v99
	v_cvt_pk_bf16_f32 v99, v100, v101
	v_pk_mul_f32 v[104:105], v[104:105], v[0:1] op_sel_hi:[1,0]
	v_cvt_pk_bf16_f32 v100, v102, v103
	v_add_co_u32_e32 v102, vcc, s70, v132
	v_cvt_pk_bf16_f32 v101, v104, v105
	v_pk_mul_f32 v[104:105], v[110:111], v[0:1] op_sel_hi:[1,0]
	s_nop 0
	v_addc_co_u32_e32 v103, vcc, 0, v130, vcc
	flat_store_dwordx4 v[102:103], v[98:101]
	v_pk_mul_f32 v[102:103], v[112:113], v[0:1] op_sel_hi:[1,0]
	s_nop 0
	v_pk_mul_f32 v[98:99], v[106:107], v[0:1] op_sel_hi:[1,0]
	v_pk_mul_f32 v[100:101], v[108:109], v[0:1] op_sel_hi:[1,0]
	v_cvt_pk_bf16_f32 v98, v98, v99
	s_nop 0
	v_cvt_pk_bf16_f32 v99, v100, v101
	v_cvt_pk_bf16_f32 v100, v104, v105
	v_cvt_pk_bf16_f32 v101, v102, v103
	flat_store_dwordx4 v[114:115], v[98:101] offset:256
	s_nop 1
	v_or_b32_e32 v98, 0x80, v146
	v_mov_b32_e32 v99, v147
	v_lshl_add_u64 v[98:99], s[48:49], 0, v[98:99]
	flat_load_dword v0, v[98:99]
	v_lshl_add_u64 v[98:99], v[132:133], 0, s[2:3]
	v_or_b32_e32 v146, 0xc0, v146
	s_mov_b64 s[2:3], 0x12000
	s_waitcnt vmcnt(0) lgkmcnt(0)
; __device__ __forceinline__ unsigned cvt_pk_bf16(float lo, float hi) { unsigned r; asm volatile("v_cvt_pk_bf16_f32 %0, %1, %2" : "=v"(r) : "v"(lo), "v"(hi)); return r; }
;     __device__ __forceinline__ void operator()(const f32x4 (&acc)[2][2][4][2], const Unit& u, int wr, int wc, int fr, int fq) const {
;     ...
;         if (u.pn < 3) {
;             const int col0 = u.pn * BM + wc * 32 + 8 * fq;
; #pragma unroll
;             for (int ai = 0; ai < 2; ++ai)
; #pragma unroll
;                 for (int m = 0; m < 4; ++m) { const size_t row = rowb + ai * HALF + m * 16; const float r = __builtin_amdgcn_rsqf(ssq_q[row] * (1.0f / 256.0f) + RMS_EPS);
; #pragma unroll
;                     for (int bj = 0; bj < 2; ++bj) { const f32x4 v0 = acc[ai][bj][m][0] * r, v1 = acc[ai][bj][m][1] * r;
;                         u32x4 w; w.x = cvt_pk_bf16(v0[0], v0[1]); w.y = cvt_pk_bf16(v0[2], v0[3]); w.z = cvt_pk_bf16(v1[0], v1[1]); w.w = cvt_pk_bf16(v1[2], v1[3]);
;                         *(u32x4*)(Oq + row * 768 + col0 + bj * HALF) = w; } }
	v_fmamk_f32 v0, v0, 0x3b800000, v231
	v_rsq_f32_e32 v0, v0
	s_nop 0
	v_pk_mul_f32 v[84:85], v[84:85], v[0:1] op_sel_hi:[1,0]
	v_pk_mul_f32 v[82:83], v[82:83], v[0:1] op_sel_hi:[1,0]
	v_pk_mul_f32 v[86:87], v[86:87], v[0:1] op_sel_hi:[1,0]
	v_cvt_pk_bf16_f32 v82, v82, v83
	v_cvt_pk_bf16_f32 v83, v84, v85
	v_pk_mul_f32 v[88:89], v[88:89], v[0:1] op_sel_hi:[1,0]
	v_cvt_pk_bf16_f32 v84, v86, v87
	v_add_co_u32_e32 v86, vcc, s71, v132
	v_cvt_pk_bf16_f32 v85, v88, v89
	v_pk_mul_f32 v[88:89], v[94:95], v[0:1] op_sel_hi:[1,0]
	s_nop 0
	v_addc_co_u32_e32 v87, vcc, 0, v130, vcc
	flat_store_dwordx4 v[86:87], v[82:85]
	v_pk_mul_f32 v[86:87], v[96:97], v[0:1] op_sel_hi:[1,0]
	s_nop 0
	v_pk_mul_f32 v[82:83], v[90:91], v[0:1] op_sel_hi:[1,0]
	v_pk_mul_f32 v[84:85], v[92:93], v[0:1] op_sel_hi:[1,0]
	v_cvt_pk_bf16_f32 v82, v82, v83
	s_nop 0
	v_cvt_pk_bf16_f32 v83, v84, v85
	v_cvt_pk_bf16_f32 v84, v88, v89
	v_cvt_pk_bf16_f32 v85, v86, v87
	flat_store_dwordx4 v[98:99], v[82:85] offset:256
	s_nop 1
	v_lshl_add_u64 v[82:83], s[48:49], 0, v[146:147]
	flat_load_dword v0, v[82:83]
	v_lshl_add_u64 v[82:83], v[132:133], 0, s[2:3]
	s_mov_b64 s[2:3], 0x30000
	s_waitcnt vmcnt(0) lgkmcnt(0)
	v_fmamk_f32 v0, v0, 0x3b800000, v231
	v_rsq_f32_e32 v0, v0
	s_nop 0
	v_pk_mul_f32 v[76:77], v[76:77], v[0:1] op_sel_hi:[1,0]
	v_pk_mul_f32 v[74:75], v[74:75], v[0:1] op_sel_hi:[1,0]
	v_pk_mul_f32 v[78:79], v[78:79], v[0:1] op_sel_hi:[1,0]
	v_cvt_pk_bf16_f32 v74, v74, v75
	v_cvt_pk_bf16_f32 v75, v76, v77
	v_pk_mul_f32 v[80:81], v[80:81], v[0:1] op_sel_hi:[1,0]
	v_cvt_pk_bf16_f32 v76, v78, v79
	v_add_co_u32_e32 v78, vcc, s29, v132
	v_cvt_pk_bf16_f32 v77, v80, v81
	v_pk_mul_f32 v[72:73], v[72:73], v[0:1] op_sel_hi:[1,0]
	s_nop 0
	v_addc_co_u32_e32 v79, vcc, 0, v130, vcc
	flat_store_dwordx4 v[78:79], v[74:77]
	v_pk_mul_f32 v[70:71], v[70:71], v[0:1] op_sel_hi:[1,0]
	s_nop 0
	v_pk_mul_f32 v[74:75], v[68:69], v[0:1] op_sel_hi:[1,0]
	v_pk_mul_f32 v[68:69], v[66:67], v[0:1] op_sel_hi:[1,0]
	v_cvt_pk_bf16_f32 v66, v70, v71
	v_cvt_pk_bf16_f32 v67, v72, v73
	s_nop 0
	v_cvt_pk_bf16_f32 v68, v68, v69
	v_cvt_pk_bf16_f32 v69, v74, v75
	flat_store_dwordx4 v[82:83], v[66:69] offset:256
	flat_load_dword v0, v[144:145] offset:512
	s_waitcnt vmcnt(0) lgkmcnt(0)
	v_fmamk_f32 v0, v0, 0x3b800000, v231
	v_rsq_f32_e32 v0, v0
	v_lshl_add_u64 v[66:67], v[132:133], 0, s[2:3]
	s_mov_b32 s2, 0x30000
	v_pk_mul_f32 v[60:61], v[60:61], v[0:1] op_sel_hi:[1,0]
	v_pk_mul_f32 v[58:59], v[58:59], v[0:1] op_sel_hi:[1,0]
	v_pk_mul_f32 v[62:63], v[62:63], v[0:1] op_sel_hi:[1,0]
	v_cvt_pk_bf16_f32 v58, v58, v59
	v_cvt_pk_bf16_f32 v59, v60, v61
	v_pk_mul_f32 v[64:65], v[64:65], v[0:1] op_sel_hi:[1,0]
	v_cvt_pk_bf16_f32 v60, v62, v63
	v_add_co_u32_e32 v62, vcc, s2, v132
	v_cvt_pk_bf16_f32 v61, v64, v65
	v_pk_mul_f32 v[56:57], v[56:57], v[0:1] op_sel_hi:[1,0]
	s_nop 0
	v_addc_co_u32_e32 v63, vcc, 0, v130, vcc
	flat_store_dwordx4 v[62:63], v[58:61]
	v_pk_mul_f32 v[54:55], v[54:55], v[0:1] op_sel_hi:[1,0]
	s_mov_b64 s[2:3], 0x36000
	v_pk_mul_f32 v[58:59], v[52:53], v[0:1] op_sel_hi:[1,0]
	v_pk_mul_f32 v[52:53], v[50:51], v[0:1] op_sel_hi:[1,0]
	v_cvt_pk_bf16_f32 v50, v54, v55
	v_cvt_pk_bf16_f32 v51, v56, v57
	s_nop 0
	v_cvt_pk_bf16_f32 v52, v52, v53
	v_cvt_pk_bf16_f32 v53, v58, v59
	flat_store_dwordx4 v[66:67], v[50:53] offset:256
	flat_load_dword v0, v[144:145] offset:576
	s_waitcnt vmcnt(0) lgkmcnt(0)
	v_fmamk_f32 v0, v0, 0x3b800000, v231
	v_rsq_f32_e32 v0, v0
	v_lshl_add_u64 v[50:51], v[132:133], 0, s[2:3]
	s_mov_b32 s2, 0x36000
	v_pk_mul_f32 v[44:45], v[44:45], v[0:1] op_sel_hi:[1,0]
	v_pk_mul_f32 v[42:43], v[42:43], v[0:1] op_sel_hi:[1,0]
	v_pk_mul_f32 v[46:47], v[46:47], v[0:1] op_sel_hi:[1,0]
	v_cvt_pk_bf16_f32 v42, v42, v43
	v_cvt_pk_bf16_f32 v43, v44, v45
	v_pk_mul_f32 v[48:49], v[48:49], v[0:1] op_sel_hi:[1,0]
	v_cvt_pk_bf16_f32 v44, v46, v47
	v_add_co_u32_e32 v46, vcc, s2, v132
	v_cvt_pk_bf16_f32 v45, v48, v49
	v_pk_mul_f32 v[40:41], v[40:41], v[0:1] op_sel_hi:[1,0]
	s_nop 0
	v_addc_co_u32_e32 v47, vcc, 0, v130, vcc
	flat_store_dwordx4 v[46:47], v[42:45]
	v_pk_mul_f32 v[38:39], v[38:39], v[0:1] op_sel_hi:[1,0]
	s_mov_b64 s[2:3], 0x3c000
	v_pk_mul_f32 v[42:43], v[36:37], v[0:1] op_sel_hi:[1,0]
	v_pk_mul_f32 v[36:37], v[34:35], v[0:1] op_sel_hi:[1,0]
	v_cvt_pk_bf16_f32 v34, v38, v39
	v_cvt_pk_bf16_f32 v35, v40, v41
	s_nop 0
	v_cvt_pk_bf16_f32 v36, v36, v37
	v_cvt_pk_bf16_f32 v37, v42, v43
	flat_store_dwordx4 v[50:51], v[34:37] offset:256
	flat_load_dword v0, v[144:145] offset:640
	s_waitcnt vmcnt(0) lgkmcnt(0)
	v_fmamk_f32 v0, v0, 0x3b800000, v231
	v_rsq_f32_e32 v0, v0
	v_lshl_add_u64 v[34:35], v[132:133], 0, s[2:3]
	s_mov_b32 s2, 0x3c000
	v_pk_mul_f32 v[28:29], v[28:29], v[0:1] op_sel_hi:[1,0]
	v_pk_mul_f32 v[26:27], v[26:27], v[0:1] op_sel_hi:[1,0]
	v_pk_mul_f32 v[30:31], v[30:31], v[0:1] op_sel_hi:[1,0]
	v_cvt_pk_bf16_f32 v26, v26, v27
	v_cvt_pk_bf16_f32 v27, v28, v29
	v_pk_mul_f32 v[32:33], v[32:33], v[0:1] op_sel_hi:[1,0]
	v_cvt_pk_bf16_f32 v28, v30, v31
	v_add_co_u32_e32 v30, vcc, s2, v132
	v_cvt_pk_bf16_f32 v29, v32, v33
	v_pk_mul_f32 v[24:25], v[24:25], v[0:1] op_sel_hi:[1,0]
	s_nop 0
	v_addc_co_u32_e32 v31, vcc, 0, v130, vcc
	flat_store_dwordx4 v[30:31], v[26:29]
	v_pk_mul_f32 v[22:23], v[22:23], v[0:1] op_sel_hi:[1,0]
	s_mov_b64 s[2:3], 0x42000
	v_pk_mul_f32 v[26:27], v[20:21], v[0:1] op_sel_hi:[1,0]
	v_pk_mul_f32 v[20:21], v[18:19], v[0:1] op_sel_hi:[1,0]
	v_cvt_pk_bf16_f32 v18, v22, v23
	v_cvt_pk_bf16_f32 v19, v24, v25
	s_nop 0
	v_cvt_pk_bf16_f32 v20, v20, v21
	v_cvt_pk_bf16_f32 v21, v26, v27
	flat_store_dwordx4 v[34:35], v[18:21] offset:256
	flat_load_dword v0, v[144:145] offset:704
	s_waitcnt vmcnt(0) lgkmcnt(0)
	v_fmamk_f32 v0, v0, 0x3b800000, v231
	v_rsq_f32_e32 v0, v0
	v_lshl_add_u64 v[18:19], v[132:133], 0, s[2:3]
	s_mov_b32 s2, 0x42000
	v_pk_mul_f32 v[12:13], v[12:13], v[0:1] op_sel_hi:[1,0]
	v_pk_mul_f32 v[10:11], v[10:11], v[0:1] op_sel_hi:[1,0]
	v_pk_mul_f32 v[14:15], v[14:15], v[0:1] op_sel_hi:[1,0]
	v_cvt_pk_bf16_f32 v10, v10, v11
	v_cvt_pk_bf16_f32 v11, v12, v13
	v_pk_mul_f32 v[16:17], v[16:17], v[0:1] op_sel_hi:[1,0]
	v_cvt_pk_bf16_f32 v12, v14, v15
	v_add_co_u32_e32 v14, vcc, s2, v132
	v_cvt_pk_bf16_f32 v13, v16, v17
	v_pk_mul_f32 v[8:9], v[8:9], v[0:1] op_sel_hi:[1,0]
	s_nop 0
	v_addc_co_u32_e32 v15, vcc, 0, v130, vcc
	flat_store_dwordx4 v[14:15], v[10:13]
	v_pk_mul_f32 v[6:7], v[6:7], v[0:1] op_sel_hi:[1,0]
	s_nop 0
	v_pk_mul_f32 v[10:11], v[4:5], v[0:1] op_sel_hi:[1,0]
	v_pk_mul_f32 v[4:5], v[2:3], v[0:1] op_sel_hi:[1,0]
	v_cvt_pk_bf16_f32 v2, v6, v7
	v_cvt_pk_bf16_f32 v3, v8, v9
	s_nop 0
	v_cvt_pk_bf16_f32 v4, v4, v5
	v_cvt_pk_bf16_f32 v5, v10, v11
	flat_store_dwordx4 v[18:19], v[2:5] offset:256
	s_andn2_b64 vcc, exec, s[40:41]
	s_mov_b64 s[2:3], -1
	s_cbranch_vccnz .LBB0_483
